# code placement: every GEMM MFMA block (32 back-to-back 8-byte MFMAs) now starts 8-byte aligned (s_nop 0 added in the preceding load segment where needed), on top of v36
# speedup vs baseline: 1.0016x; 1.0016x over previous
.Lpeela:
	ds_read_b128 v[130:133], v208
	ds_read_b128 v[134:137], v208 offset:1024
	ds_read_b128 v[138:141], v208 offset:2048
	ds_read_b128 v[142:145], v208 offset:3072
	ds_read_b128 v[146:149], v209
	ds_read_b128 v[150:153], v209 offset:1024
	ds_read_b128 v[154:157], v209 offset:2048
	ds_read_b128 v[158:161], v209 offset:3072
	s_add_u32 s52, s50, 0xfff00080
	s_addc_u32 s53, s51, -1
	s_cmp_eq_u32 s89, 60
	s_cselect_b32 s55, s43, s53
	s_cselect_b32 s54, s85, s52
	s_cselect_b32 s53, s41, s88
	s_cselect_b32 s52, s86, s87
	v_lshl_add_u64 v[204:205], s[50:51], 0, v[192:193]
	s_add_i32 m0, s56, 0xc000
	ds_read_b128 v[162:165], v210
	ds_read_b128 v[166:169], v210 offset:1024
	ds_read_b128 v[170:173], v210 offset:2048
	ds_read_b128 v[174:177], v210 offset:3072
	ds_read_b128 v[200:203], v210 offset:4096
	ds_read_b128 v[212:215], v210 offset:5120
	ds_read_b128 v[216:219], v210 offset:6144
	ds_read_b128 v[224:227], v210 offset:7168
	global_load_lds_dwordx4 v[204:205], off
	v_lshl_add_u64 v[204:205], s[50:51], 0, v[194:195]
	s_add_i32 m0, s56, 0xe000
	s_nop 0
	global_load_lds_dwordx4 v[204:205], off
	s_waitcnt vmcnt(8)
	s_waitcnt lgkmcnt(0)
	s_nop 0
	s_setprio 1
	s_barrier
	v_mfma_f32_16x16x32_bf16 v[126:129], v[130:133], v[162:165], 0
	v_mfma_f32_16x16x32_bf16 v[122:125], v[138:141], v[162:165], 0
	v_mfma_f32_16x16x32_bf16 v[110:113], v[130:133], v[170:173], 0
	v_mfma_f32_16x16x32_bf16 v[106:109], v[138:141], v[170:173], 0
	v_mfma_f32_16x16x32_bf16 v[94:97], v[130:133], v[200:203], 0
	v_mfma_f32_16x16x32_bf16 v[90:93], v[138:141], v[200:203], 0
	v_mfma_f32_16x16x32_bf16 v[78:81], v[130:133], v[216:219], 0
	v_mfma_f32_16x16x32_bf16 v[74:77], v[138:141], v[216:219], 0
	v_mfma_f32_16x16x32_bf16 v[126:129], v[134:137], v[166:169], v[126:129]
	v_mfma_f32_16x16x32_bf16 v[122:125], v[142:145], v[166:169], v[122:125]
	v_mfma_f32_16x16x32_bf16 v[110:113], v[134:137], v[174:177], v[110:113]
	v_mfma_f32_16x16x32_bf16 v[106:109], v[142:145], v[174:177], v[106:109]
	v_mfma_f32_16x16x32_bf16 v[94:97], v[134:137], v[212:215], v[94:97]
	v_mfma_f32_16x16x32_bf16 v[90:93], v[142:145], v[212:215], v[90:93]
	v_mfma_f32_16x16x32_bf16 v[78:81], v[134:137], v[224:227], v[78:81]
	v_mfma_f32_16x16x32_bf16 v[74:77], v[142:145], v[224:227], v[74:77]
	v_mfma_f32_16x16x32_bf16 v[118:121], v[146:149], v[162:165], 0
	v_mfma_f32_16x16x32_bf16 v[114:117], v[154:157], v[162:165], 0
	v_mfma_f32_16x16x32_bf16 v[102:105], v[146:149], v[170:173], 0
	v_mfma_f32_16x16x32_bf16 v[98:101], v[154:157], v[170:173], 0
	v_mfma_f32_16x16x32_bf16 v[86:89], v[146:149], v[200:203], 0
	v_mfma_f32_16x16x32_bf16 v[82:85], v[154:157], v[200:203], 0
	v_mfma_f32_16x16x32_bf16 v[70:73], v[146:149], v[216:219], 0
	v_mfma_f32_16x16x32_bf16 v[66:69], v[154:157], v[216:219], 0
	v_mfma_f32_16x16x32_bf16 v[118:121], v[150:153], v[166:169], v[118:121]
	v_mfma_f32_16x16x32_bf16 v[114:117], v[158:161], v[166:169], v[114:117]
	v_mfma_f32_16x16x32_bf16 v[102:105], v[150:153], v[174:177], v[102:105]
	v_mfma_f32_16x16x32_bf16 v[98:101], v[158:161], v[174:177], v[98:101]
	v_mfma_f32_16x16x32_bf16 v[86:89], v[150:153], v[212:215], v[86:89]
	v_mfma_f32_16x16x32_bf16 v[82:85], v[158:161], v[212:215], v[82:85]
	v_mfma_f32_16x16x32_bf16 v[70:73], v[150:153], v[224:227], v[70:73]
	v_mfma_f32_16x16x32_bf16 v[66:69], v[158:161], v[224:227], v[66:69]
	s_barrier
	s_setprio 0
	s_add_i32 s90, s65, s31
	v_lshl_add_u64 v[204:205], s[52:53], 0, v[182:183]
	s_mov_b32 m0, s90
	ds_read_b128 v[162:165], v210 offset:16384
	ds_read_b128 v[166:169], v210 offset:17408
	ds_read_b128 v[170:173], v210 offset:18432
	ds_read_b128 v[174:177], v210 offset:19456
	ds_read_b128 v[200:203], v210 offset:20480
	ds_read_b128 v[212:215], v210 offset:21504
	ds_read_b128 v[216:219], v210 offset:22528
	ds_read_b128 v[224:227], v210 offset:23552
	global_load_lds_dwordx4 v[204:205], off
	s_add_i32 m0, s90, 0x2000
	s_add_u32 s90, s52, 0x100000
	v_lshl_add_u64 v[220:221], s[52:53], 0, v[178:179]
	s_addc_u32 s91, s53, 0
	s_add_i32 s92, s66, s31
	global_load_lds_dwordx4 v[220:221], off
	v_lshl_add_u64 v[228:229], s[90:91], 0, v[182:183]
	s_mov_b32 m0, s92
	v_lshl_add_u64 v[230:231], s[54:55], 0, v[180:181]
	global_load_lds_dwordx4 v[228:229], off
	v_lshl_add_u64 v[228:229], s[90:91], 0, v[178:179]
	s_add_i32 m0, s92, 0x2000
	s_nop 0
	global_load_lds_dwordx4 v[228:229], off
	v_lshl_add_u64 v[228:229], s[54:55], 0, v[184:185]
	s_mov_b32 m0, s56
	s_nop 0
	global_load_lds_dwordx4 v[228:229], off
	s_mov_b32 m0, s57
	s_nop 0
	global_load_lds_dwordx4 v[230:231], off
	s_waitcnt vmcnt(8)
	s_waitcnt lgkmcnt(0)
	s_setprio 1
	s_barrier
	v_mfma_f32_16x16x32_bf16 v[62:65], v[130:133], v[162:165], 0
	v_mfma_f32_16x16x32_bf16 v[58:61], v[138:141], v[162:165], 0
	v_mfma_f32_16x16x32_bf16 v[50:53], v[130:133], v[170:173], 0
	v_mfma_f32_16x16x32_bf16 v[42:45], v[138:141], v[170:173], 0
	v_mfma_f32_16x16x32_bf16 v[34:37], v[130:133], v[200:203], 0
	v_mfma_f32_16x16x32_bf16 v[26:29], v[138:141], v[200:203], 0
	v_mfma_f32_16x16x32_bf16 v[18:21], v[130:133], v[216:219], 0
	v_mfma_f32_16x16x32_bf16 v[10:13], v[138:141], v[216:219], 0
	v_mfma_f32_16x16x32_bf16 v[62:65], v[134:137], v[166:169], v[62:65]
	v_mfma_f32_16x16x32_bf16 v[58:61], v[142:145], v[166:169], v[58:61]
	v_mfma_f32_16x16x32_bf16 v[50:53], v[134:137], v[174:177], v[50:53]
	v_mfma_f32_16x16x32_bf16 v[42:45], v[142:145], v[174:177], v[42:45]
	v_mfma_f32_16x16x32_bf16 v[34:37], v[134:137], v[212:215], v[34:37]
	v_mfma_f32_16x16x32_bf16 v[26:29], v[142:145], v[212:215], v[26:29]
	v_mfma_f32_16x16x32_bf16 v[18:21], v[134:137], v[224:227], v[18:21]
	v_mfma_f32_16x16x32_bf16 v[10:13], v[142:145], v[224:227], v[10:13]
	v_mfma_f32_16x16x32_bf16 v[54:57], v[146:149], v[162:165], 0
	v_mfma_f32_16x16x32_bf16 v[46:49], v[154:157], v[162:165], 0
	v_mfma_f32_16x16x32_bf16 v[38:41], v[146:149], v[170:173], 0
	v_mfma_f32_16x16x32_bf16 v[30:33], v[154:157], v[170:173], 0
	v_mfma_f32_16x16x32_bf16 v[22:25], v[146:149], v[200:203], 0
	v_mfma_f32_16x16x32_bf16 v[14:17], v[154:157], v[200:203], 0
	v_mfma_f32_16x16x32_bf16 v[6:9], v[146:149], v[216:219], 0
	v_mfma_f32_16x16x32_bf16 v[2:5], v[154:157], v[216:219], 0
	v_mfma_f32_16x16x32_bf16 v[54:57], v[150:153], v[166:169], v[54:57]
	v_mfma_f32_16x16x32_bf16 v[46:49], v[158:161], v[166:169], v[46:49]
	v_mfma_f32_16x16x32_bf16 v[38:41], v[150:153], v[174:177], v[38:41]
	v_mfma_f32_16x16x32_bf16 v[30:33], v[158:161], v[174:177], v[30:33]
	v_mfma_f32_16x16x32_bf16 v[22:25], v[150:153], v[212:215], v[22:25]
	v_mfma_f32_16x16x32_bf16 v[14:17], v[158:161], v[212:215], v[14:17]
	v_mfma_f32_16x16x32_bf16 v[6:9], v[150:153], v[224:227], v[6:9]
	v_mfma_f32_16x16x32_bf16 v[2:5], v[158:161], v[224:227], v[2:5]
	s_barrier
	s_setprio 0
	s_add_i32 s90, 0, 0x18000
	s_add_i32 s91, 0, 0x1c000
	v_add_u32_e32 v142, s90, v189
	v_add_u32_e32 v158, s91, v189
	ds_read_b128 v[130:133], v142
	ds_read_b128 v[134:137], v142 offset:1024
	ds_read_b128 v[138:141], v142 offset:2048
	ds_read_b128 v[142:145], v142 offset:3072
	ds_read_b128 v[146:149], v158
	ds_read_b128 v[150:153], v158 offset:1024
	ds_read_b128 v[154:157], v158 offset:2048
	ds_read_b128 v[158:161], v158 offset:3072
	s_add_u32 s54, s54, 0x100000
	s_addc_u32 s55, s55, 0
	s_mov_b32 m0, s58
	v_lshl_add_u64 v[232:233], s[54:55], 0, v[184:185]
	ds_read_b128 v[162:165], v210 offset:32768
	ds_read_b128 v[166:169], v210 offset:33792
	ds_read_b128 v[170:173], v210 offset:34816
	ds_read_b128 v[174:177], v210 offset:35840
	ds_read_b128 v[200:203], v210 offset:36864
	ds_read_b128 v[212:215], v210 offset:37888
	ds_read_b128 v[216:219], v210 offset:38912
	ds_read_b128 v[224:227], v210 offset:39936
	global_load_lds_dwordx4 v[232:233], off
	v_lshl_add_u64 v[232:233], s[54:55], 0, v[180:181]
	s_mov_b32 m0, s59
	s_nop 0
	global_load_lds_dwordx4 v[232:233], off
	s_waitcnt vmcnt(8)
	s_waitcnt lgkmcnt(0)
	s_setprio 1
	s_barrier
	v_mfma_f32_16x16x32_bf16 v[126:129], v[130:133], v[162:165], v[126:129]
	v_mfma_f32_16x16x32_bf16 v[122:125], v[138:141], v[162:165], v[122:125]
	v_mfma_f32_16x16x32_bf16 v[110:113], v[130:133], v[170:173], v[110:113]
	v_mfma_f32_16x16x32_bf16 v[106:109], v[138:141], v[170:173], v[106:109]
	v_mfma_f32_16x16x32_bf16 v[94:97], v[130:133], v[200:203], v[94:97]
	v_mfma_f32_16x16x32_bf16 v[90:93], v[138:141], v[200:203], v[90:93]
	v_mfma_f32_16x16x32_bf16 v[78:81], v[130:133], v[216:219], v[78:81]
	v_mfma_f32_16x16x32_bf16 v[74:77], v[138:141], v[216:219], v[74:77]
	v_mfma_f32_16x16x32_bf16 v[126:129], v[134:137], v[166:169], v[126:129]
	v_mfma_f32_16x16x32_bf16 v[122:125], v[142:145], v[166:169], v[122:125]
	v_mfma_f32_16x16x32_bf16 v[110:113], v[134:137], v[174:177], v[110:113]
	v_mfma_f32_16x16x32_bf16 v[106:109], v[142:145], v[174:177], v[106:109]
	v_mfma_f32_16x16x32_bf16 v[94:97], v[134:137], v[212:215], v[94:97]
	v_mfma_f32_16x16x32_bf16 v[90:93], v[142:145], v[212:215], v[90:93]
	v_mfma_f32_16x16x32_bf16 v[78:81], v[134:137], v[224:227], v[78:81]
	v_mfma_f32_16x16x32_bf16 v[74:77], v[142:145], v[224:227], v[74:77]
	v_mfma_f32_16x16x32_bf16 v[118:121], v[146:149], v[162:165], v[118:121]
	v_mfma_f32_16x16x32_bf16 v[114:117], v[154:157], v[162:165], v[114:117]
	v_mfma_f32_16x16x32_bf16 v[102:105], v[146:149], v[170:173], v[102:105]
	v_mfma_f32_16x16x32_bf16 v[98:101], v[154:157], v[170:173], v[98:101]
	v_mfma_f32_16x16x32_bf16 v[86:89], v[146:149], v[200:203], v[86:89]
	v_mfma_f32_16x16x32_bf16 v[82:85], v[154:157], v[200:203], v[82:85]
	v_mfma_f32_16x16x32_bf16 v[70:73], v[146:149], v[216:219], v[70:73]
	v_mfma_f32_16x16x32_bf16 v[66:69], v[154:157], v[216:219], v[66:69]
	v_mfma_f32_16x16x32_bf16 v[118:121], v[150:153], v[166:169], v[118:121]
	v_mfma_f32_16x16x32_bf16 v[114:117], v[158:161], v[166:169], v[114:117]
	v_mfma_f32_16x16x32_bf16 v[102:105], v[150:153], v[174:177], v[102:105]
	v_mfma_f32_16x16x32_bf16 v[98:101], v[158:161], v[174:177], v[98:101]
	v_mfma_f32_16x16x32_bf16 v[86:89], v[150:153], v[212:215], v[86:89]
	v_mfma_f32_16x16x32_bf16 v[82:85], v[158:161], v[212:215], v[82:85]
	v_mfma_f32_16x16x32_bf16 v[70:73], v[150:153], v[224:227], v[70:73]
	v_mfma_f32_16x16x32_bf16 v[66:69], v[158:161], v[224:227], v[66:69]
	s_barrier
	s_setprio 0
	s_add_i32 s54, s90, s31
	v_lshl_add_u64 v[204:205], v[204:205], 0, s[8:9]
	s_mov_b32 m0, s54
	ds_read_b128 v[162:165], v210 offset:49152
	ds_read_b128 v[166:169], v210 offset:50176
	ds_read_b128 v[170:173], v210 offset:51200
	ds_read_b128 v[174:177], v210 offset:52224
	ds_read_b128 v[200:203], v210 offset:53248
	ds_read_b128 v[212:215], v210 offset:54272
	ds_read_b128 v[216:219], v210 offset:55296
	ds_read_b128 v[224:227], v210 offset:56320
	global_load_lds_dwordx4 v[204:205], off
	s_add_i32 m0, s54, 0x2000
	s_add_u32 s52, s52, 0x100080
	v_lshl_add_u64 v[204:205], v[220:221], 0, s[8:9]
	s_addc_u32 s53, s53, 0
	s_add_i32 s54, s91, s31
	global_load_lds_dwordx4 v[204:205], off
	v_lshl_add_u64 v[204:205], s[52:53], 0, v[182:183]
	s_mov_b32 m0, s54
	s_nop 0
	global_load_lds_dwordx4 v[204:205], off
	v_lshl_add_u64 v[204:205], s[52:53], 0, v[178:179]
	s_add_i32 m0, s54, 0x2000
	s_nop 0
	global_load_lds_dwordx4 v[204:205], off
	v_lshl_add_u64 v[204:205], v[228:229], 0, s[8:9]
	s_mov_b32 m0, s62
	s_nop 0
	global_load_lds_dwordx4 v[204:205], off
	v_lshl_add_u64 v[204:205], v[230:231], 0, s[8:9]
	s_mov_b32 m0, s63
	s_nop 0
	global_load_lds_dwordx4 v[204:205], off
	s_waitcnt vmcnt(8)
	s_waitcnt lgkmcnt(0)
	s_nop 0
	s_setprio 1
	s_barrier
	v_mfma_f32_16x16x32_bf16 v[62:65], v[130:133], v[162:165], v[62:65]
	v_mfma_f32_16x16x32_bf16 v[58:61], v[138:141], v[162:165], v[58:61]
	v_mfma_f32_16x16x32_bf16 v[50:53], v[130:133], v[170:173], v[50:53]
	v_mfma_f32_16x16x32_bf16 v[42:45], v[138:141], v[170:173], v[42:45]
	v_mfma_f32_16x16x32_bf16 v[34:37], v[130:133], v[200:203], v[34:37]
	v_mfma_f32_16x16x32_bf16 v[26:29], v[138:141], v[200:203], v[26:29]
	v_mfma_f32_16x16x32_bf16 v[18:21], v[130:133], v[216:219], v[18:21]
	v_mfma_f32_16x16x32_bf16 v[10:13], v[138:141], v[216:219], v[10:13]
	v_mfma_f32_16x16x32_bf16 v[62:65], v[134:137], v[166:169], v[62:65]
	v_mfma_f32_16x16x32_bf16 v[58:61], v[142:145], v[166:169], v[58:61]
	v_mfma_f32_16x16x32_bf16 v[50:53], v[134:137], v[174:177], v[50:53]
	v_mfma_f32_16x16x32_bf16 v[42:45], v[142:145], v[174:177], v[42:45]
	v_mfma_f32_16x16x32_bf16 v[34:37], v[134:137], v[212:215], v[34:37]
	v_mfma_f32_16x16x32_bf16 v[26:29], v[142:145], v[212:215], v[26:29]
	v_mfma_f32_16x16x32_bf16 v[18:21], v[134:137], v[224:227], v[18:21]
	v_mfma_f32_16x16x32_bf16 v[10:13], v[142:145], v[224:227], v[10:13]
	v_mfma_f32_16x16x32_bf16 v[54:57], v[146:149], v[162:165], v[54:57]
	v_mfma_f32_16x16x32_bf16 v[46:49], v[154:157], v[162:165], v[46:49]
	v_mfma_f32_16x16x32_bf16 v[38:41], v[146:149], v[170:173], v[38:41]
	v_mfma_f32_16x16x32_bf16 v[30:33], v[154:157], v[170:173], v[30:33]
	v_mfma_f32_16x16x32_bf16 v[22:25], v[146:149], v[200:203], v[22:25]
	v_mfma_f32_16x16x32_bf16 v[14:17], v[154:157], v[200:203], v[14:17]
	v_mfma_f32_16x16x32_bf16 v[6:9], v[146:149], v[216:219], v[6:9]
	v_mfma_f32_16x16x32_bf16 v[2:5], v[154:157], v[216:219], v[2:5]
	v_mfma_f32_16x16x32_bf16 v[54:57], v[150:153], v[166:169], v[54:57]
	v_mfma_f32_16x16x32_bf16 v[46:49], v[158:161], v[166:169], v[46:49]
	v_mfma_f32_16x16x32_bf16 v[38:41], v[150:153], v[174:177], v[38:41]
	v_mfma_f32_16x16x32_bf16 v[30:33], v[158:161], v[174:177], v[30:33]
	v_mfma_f32_16x16x32_bf16 v[22:25], v[150:153], v[212:215], v[22:25]
	v_mfma_f32_16x16x32_bf16 v[14:17], v[158:161], v[212:215], v[14:17]
	v_mfma_f32_16x16x32_bf16 v[6:9], v[150:153], v[224:227], v[6:9]
	v_mfma_f32_16x16x32_bf16 v[2:5], v[158:161], v[224:227], v[2:5]
	s_barrier
	s_setprio 0
	s_add_i32 s89, s89, 2
	s_add_u32 s50, s50, 0x100
	s_addc_u32 s51, s51, 0
	s_add_u32 s87, s87, 0x100
	s_addc_u32 s88, s88, 0
.LBB0_224:
	ds_read_b128 v[130:133], v208
	ds_read_b128 v[134:137], v208 offset:1024
	ds_read_b128 v[138:141], v208 offset:2048
	ds_read_b128 v[142:145], v208 offset:3072
	ds_read_b128 v[146:149], v209
	ds_read_b128 v[150:153], v209 offset:1024
	ds_read_b128 v[154:157], v209 offset:2048
	ds_read_b128 v[158:161], v209 offset:3072
	s_add_u32 s52, s50, 0xfff00080
	s_addc_u32 s53, s51, -1
	s_cmp_eq_u32 s89, 60
	s_cselect_b32 s55, s43, s53
	s_cselect_b32 s54, s85, s52
	s_cselect_b32 s53, s41, s88
	s_cselect_b32 s52, s86, s87
	v_lshl_add_u64 v[204:205], s[50:51], 0, v[192:193]
	s_add_i32 m0, s56, 0xc000
	ds_read_b128 v[162:165], v210
	ds_read_b128 v[166:169], v210 offset:1024
	ds_read_b128 v[170:173], v210 offset:2048
	ds_read_b128 v[174:177], v210 offset:3072
	ds_read_b128 v[200:203], v210 offset:4096
	ds_read_b128 v[212:215], v210 offset:5120
	ds_read_b128 v[216:219], v210 offset:6144
	ds_read_b128 v[224:227], v210 offset:7168
	global_load_lds_dwordx4 v[204:205], off
	v_lshl_add_u64 v[204:205], s[50:51], 0, v[194:195]
	s_add_i32 m0, s56, 0xe000
	s_nop 0
	global_load_lds_dwordx4 v[204:205], off
	s_waitcnt vmcnt(8)
	s_waitcnt lgkmcnt(0)
	s_setprio 1
	s_barrier
	v_mfma_f32_16x16x32_bf16 v[126:129], v[130:133], v[162:165], v[126:129]
	v_mfma_f32_16x16x32_bf16 v[122:125], v[138:141], v[162:165], v[122:125]
	v_mfma_f32_16x16x32_bf16 v[110:113], v[130:133], v[170:173], v[110:113]
	v_mfma_f32_16x16x32_bf16 v[106:109], v[138:141], v[170:173], v[106:109]
	v_mfma_f32_16x16x32_bf16 v[94:97], v[130:133], v[200:203], v[94:97]
	v_mfma_f32_16x16x32_bf16 v[90:93], v[138:141], v[200:203], v[90:93]
	v_mfma_f32_16x16x32_bf16 v[78:81], v[130:133], v[216:219], v[78:81]
	v_mfma_f32_16x16x32_bf16 v[74:77], v[138:141], v[216:219], v[74:77]
	v_mfma_f32_16x16x32_bf16 v[126:129], v[134:137], v[166:169], v[126:129]
	v_mfma_f32_16x16x32_bf16 v[122:125], v[142:145], v[166:169], v[122:125]
	v_mfma_f32_16x16x32_bf16 v[110:113], v[134:137], v[174:177], v[110:113]
	v_mfma_f32_16x16x32_bf16 v[106:109], v[142:145], v[174:177], v[106:109]
	v_mfma_f32_16x16x32_bf16 v[94:97], v[134:137], v[212:215], v[94:97]
	v_mfma_f32_16x16x32_bf16 v[90:93], v[142:145], v[212:215], v[90:93]
	v_mfma_f32_16x16x32_bf16 v[78:81], v[134:137], v[224:227], v[78:81]
	v_mfma_f32_16x16x32_bf16 v[74:77], v[142:145], v[224:227], v[74:77]
	v_mfma_f32_16x16x32_bf16 v[118:121], v[146:149], v[162:165], v[118:121]
	v_mfma_f32_16x16x32_bf16 v[114:117], v[154:157], v[162:165], v[114:117]
	v_mfma_f32_16x16x32_bf16 v[102:105], v[146:149], v[170:173], v[102:105]
	v_mfma_f32_16x16x32_bf16 v[98:101], v[154:157], v[170:173], v[98:101]
	v_mfma_f32_16x16x32_bf16 v[86:89], v[146:149], v[200:203], v[86:89]
	v_mfma_f32_16x16x32_bf16 v[82:85], v[154:157], v[200:203], v[82:85]
	v_mfma_f32_16x16x32_bf16 v[70:73], v[146:149], v[216:219], v[70:73]
	v_mfma_f32_16x16x32_bf16 v[66:69], v[154:157], v[216:219], v[66:69]
	v_mfma_f32_16x16x32_bf16 v[118:121], v[150:153], v[166:169], v[118:121]
	v_mfma_f32_16x16x32_bf16 v[114:117], v[158:161], v[166:169], v[114:117]
	v_mfma_f32_16x16x32_bf16 v[102:105], v[150:153], v[174:177], v[102:105]
	v_mfma_f32_16x16x32_bf16 v[98:101], v[158:161], v[174:177], v[98:101]
	v_mfma_f32_16x16x32_bf16 v[86:89], v[150:153], v[212:215], v[86:89]
	v_mfma_f32_16x16x32_bf16 v[82:85], v[158:161], v[212:215], v[82:85]
	v_mfma_f32_16x16x32_bf16 v[70:73], v[150:153], v[224:227], v[70:73]
	v_mfma_f32_16x16x32_bf16 v[66:69], v[158:161], v[224:227], v[66:69]
	s_barrier
	s_setprio 0
	s_add_i32 s90, s65, s31
	v_lshl_add_u64 v[204:205], s[52:53], 0, v[182:183]
	s_mov_b32 m0, s90
	ds_read_b128 v[162:165], v210 offset:16384
	ds_read_b128 v[166:169], v210 offset:17408
	ds_read_b128 v[170:173], v210 offset:18432
	ds_read_b128 v[174:177], v210 offset:19456
	ds_read_b128 v[200:203], v210 offset:20480
	ds_read_b128 v[212:215], v210 offset:21504
	ds_read_b128 v[216:219], v210 offset:22528
	ds_read_b128 v[224:227], v210 offset:23552
	global_load_lds_dwordx4 v[204:205], off
	s_add_i32 m0, s90, 0x2000
	s_add_u32 s90, s52, 0x100000
	v_lshl_add_u64 v[220:221], s[52:53], 0, v[178:179]
	s_addc_u32 s91, s53, 0
	s_add_i32 s92, s66, s31
	global_load_lds_dwordx4 v[220:221], off
	v_lshl_add_u64 v[228:229], s[90:91], 0, v[182:183]
	s_mov_b32 m0, s92
	v_lshl_add_u64 v[230:231], s[54:55], 0, v[180:181]
	global_load_lds_dwordx4 v[228:229], off
	v_lshl_add_u64 v[228:229], s[90:91], 0, v[178:179]
	s_add_i32 m0, s92, 0x2000
	s_nop 0
	global_load_lds_dwordx4 v[228:229], off
	v_lshl_add_u64 v[228:229], s[54:55], 0, v[184:185]
	s_mov_b32 m0, s56
	s_nop 0
	global_load_lds_dwordx4 v[228:229], off
	s_mov_b32 m0, s57
	s_nop 0
	global_load_lds_dwordx4 v[230:231], off
	s_waitcnt vmcnt(8)
	s_waitcnt lgkmcnt(0)
	s_setprio 1
	s_barrier
	v_mfma_f32_16x16x32_bf16 v[62:65], v[130:133], v[162:165], v[62:65]
	v_mfma_f32_16x16x32_bf16 v[58:61], v[138:141], v[162:165], v[58:61]
	v_mfma_f32_16x16x32_bf16 v[50:53], v[130:133], v[170:173], v[50:53]
	v_mfma_f32_16x16x32_bf16 v[42:45], v[138:141], v[170:173], v[42:45]
	v_mfma_f32_16x16x32_bf16 v[34:37], v[130:133], v[200:203], v[34:37]
	v_mfma_f32_16x16x32_bf16 v[26:29], v[138:141], v[200:203], v[26:29]
	v_mfma_f32_16x16x32_bf16 v[18:21], v[130:133], v[216:219], v[18:21]
	v_mfma_f32_16x16x32_bf16 v[10:13], v[138:141], v[216:219], v[10:13]
	v_mfma_f32_16x16x32_bf16 v[62:65], v[134:137], v[166:169], v[62:65]
	v_mfma_f32_16x16x32_bf16 v[58:61], v[142:145], v[166:169], v[58:61]
	v_mfma_f32_16x16x32_bf16 v[50:53], v[134:137], v[174:177], v[50:53]
	v_mfma_f32_16x16x32_bf16 v[42:45], v[142:145], v[174:177], v[42:45]
	v_mfma_f32_16x16x32_bf16 v[34:37], v[134:137], v[212:215], v[34:37]
	v_mfma_f32_16x16x32_bf16 v[26:29], v[142:145], v[212:215], v[26:29]
	v_mfma_f32_16x16x32_bf16 v[18:21], v[134:137], v[224:227], v[18:21]
	v_mfma_f32_16x16x32_bf16 v[10:13], v[142:145], v[224:227], v[10:13]
	v_mfma_f32_16x16x32_bf16 v[54:57], v[146:149], v[162:165], v[54:57]
	v_mfma_f32_16x16x32_bf16 v[46:49], v[154:157], v[162:165], v[46:49]
	v_mfma_f32_16x16x32_bf16 v[38:41], v[146:149], v[170:173], v[38:41]
	v_mfma_f32_16x16x32_bf16 v[30:33], v[154:157], v[170:173], v[30:33]
	v_mfma_f32_16x16x32_bf16 v[22:25], v[146:149], v[200:203], v[22:25]
	v_mfma_f32_16x16x32_bf16 v[14:17], v[154:157], v[200:203], v[14:17]
	v_mfma_f32_16x16x32_bf16 v[6:9], v[146:149], v[216:219], v[6:9]
	v_mfma_f32_16x16x32_bf16 v[2:5], v[154:157], v[216:219], v[2:5]
	v_mfma_f32_16x16x32_bf16 v[54:57], v[150:153], v[166:169], v[54:57]
	v_mfma_f32_16x16x32_bf16 v[46:49], v[158:161], v[166:169], v[46:49]
	v_mfma_f32_16x16x32_bf16 v[38:41], v[150:153], v[174:177], v[38:41]
	v_mfma_f32_16x16x32_bf16 v[30:33], v[158:161], v[174:177], v[30:33]
	v_mfma_f32_16x16x32_bf16 v[22:25], v[150:153], v[212:215], v[22:25]
	v_mfma_f32_16x16x32_bf16 v[14:17], v[158:161], v[212:215], v[14:17]
	v_mfma_f32_16x16x32_bf16 v[6:9], v[150:153], v[224:227], v[6:9]
	v_mfma_f32_16x16x32_bf16 v[2:5], v[158:161], v[224:227], v[2:5]
	s_barrier
	s_setprio 0
	s_add_i32 s90, 0, 0x18000
	s_add_i32 s91, 0, 0x1c000
	v_add_u32_e32 v142, s90, v189
	v_add_u32_e32 v158, s91, v189
	ds_read_b128 v[130:133], v142
	ds_read_b128 v[134:137], v142 offset:1024
	ds_read_b128 v[138:141], v142 offset:2048
	ds_read_b128 v[142:145], v142 offset:3072
	ds_read_b128 v[146:149], v158
	ds_read_b128 v[150:153], v158 offset:1024
	ds_read_b128 v[154:157], v158 offset:2048
	ds_read_b128 v[158:161], v158 offset:3072
	s_add_u32 s54, s54, 0x100000
	s_addc_u32 s55, s55, 0
	s_mov_b32 m0, s58
	v_lshl_add_u64 v[232:233], s[54:55], 0, v[184:185]
	ds_read_b128 v[162:165], v210 offset:32768
	ds_read_b128 v[166:169], v210 offset:33792
	ds_read_b128 v[170:173], v210 offset:34816
	ds_read_b128 v[174:177], v210 offset:35840
	ds_read_b128 v[200:203], v210 offset:36864
	ds_read_b128 v[212:215], v210 offset:37888
	ds_read_b128 v[216:219], v210 offset:38912
	ds_read_b128 v[224:227], v210 offset:39936
	global_load_lds_dwordx4 v[232:233], off
	v_lshl_add_u64 v[232:233], s[54:55], 0, v[180:181]
	s_mov_b32 m0, s59
	s_nop 0
	global_load_lds_dwordx4 v[232:233], off
	s_waitcnt vmcnt(8)
	s_waitcnt lgkmcnt(0)
	s_setprio 1
	s_barrier
	v_mfma_f32_16x16x32_bf16 v[126:129], v[130:133], v[162:165], v[126:129]
	v_mfma_f32_16x16x32_bf16 v[122:125], v[138:141], v[162:165], v[122:125]
	v_mfma_f32_16x16x32_bf16 v[110:113], v[130:133], v[170:173], v[110:113]
	v_mfma_f32_16x16x32_bf16 v[106:109], v[138:141], v[170:173], v[106:109]
	v_mfma_f32_16x16x32_bf16 v[94:97], v[130:133], v[200:203], v[94:97]
	v_mfma_f32_16x16x32_bf16 v[90:93], v[138:141], v[200:203], v[90:93]
	v_mfma_f32_16x16x32_bf16 v[78:81], v[130:133], v[216:219], v[78:81]
	v_mfma_f32_16x16x32_bf16 v[74:77], v[138:141], v[216:219], v[74:77]
	v_mfma_f32_16x16x32_bf16 v[126:129], v[134:137], v[166:169], v[126:129]
	v_mfma_f32_16x16x32_bf16 v[122:125], v[142:145], v[166:169], v[122:125]
	v_mfma_f32_16x16x32_bf16 v[110:113], v[134:137], v[174:177], v[110:113]
	v_mfma_f32_16x16x32_bf16 v[106:109], v[142:145], v[174:177], v[106:109]
	v_mfma_f32_16x16x32_bf16 v[94:97], v[134:137], v[212:215], v[94:97]
	v_mfma_f32_16x16x32_bf16 v[90:93], v[142:145], v[212:215], v[90:93]
	v_mfma_f32_16x16x32_bf16 v[78:81], v[134:137], v[224:227], v[78:81]
	v_mfma_f32_16x16x32_bf16 v[74:77], v[142:145], v[224:227], v[74:77]
	v_mfma_f32_16x16x32_bf16 v[118:121], v[146:149], v[162:165], v[118:121]
	v_mfma_f32_16x16x32_bf16 v[114:117], v[154:157], v[162:165], v[114:117]
	v_mfma_f32_16x16x32_bf16 v[102:105], v[146:149], v[170:173], v[102:105]
	v_mfma_f32_16x16x32_bf16 v[98:101], v[154:157], v[170:173], v[98:101]
	v_mfma_f32_16x16x32_bf16 v[86:89], v[146:149], v[200:203], v[86:89]
	v_mfma_f32_16x16x32_bf16 v[82:85], v[154:157], v[200:203], v[82:85]
	v_mfma_f32_16x16x32_bf16 v[70:73], v[146:149], v[216:219], v[70:73]
	v_mfma_f32_16x16x32_bf16 v[66:69], v[154:157], v[216:219], v[66:69]
	v_mfma_f32_16x16x32_bf16 v[118:121], v[150:153], v[166:169], v[118:121]
	v_mfma_f32_16x16x32_bf16 v[114:117], v[158:161], v[166:169], v[114:117]
	v_mfma_f32_16x16x32_bf16 v[102:105], v[150:153], v[174:177], v[102:105]
	v_mfma_f32_16x16x32_bf16 v[98:101], v[158:161], v[174:177], v[98:101]
	v_mfma_f32_16x16x32_bf16 v[86:89], v[150:153], v[212:215], v[86:89]
	v_mfma_f32_16x16x32_bf16 v[82:85], v[158:161], v[212:215], v[82:85]
	v_mfma_f32_16x16x32_bf16 v[70:73], v[150:153], v[224:227], v[70:73]
	v_mfma_f32_16x16x32_bf16 v[66:69], v[158:161], v[224:227], v[66:69]
	s_barrier
	s_setprio 0
	s_add_i32 s54, s90, s31
	v_lshl_add_u64 v[204:205], v[204:205], 0, s[8:9]
	s_mov_b32 m0, s54
	ds_read_b128 v[162:165], v210 offset:49152
	ds_read_b128 v[166:169], v210 offset:50176
	ds_read_b128 v[170:173], v210 offset:51200
	ds_read_b128 v[174:177], v210 offset:52224
	ds_read_b128 v[200:203], v210 offset:53248
	ds_read_b128 v[212:215], v210 offset:54272
	ds_read_b128 v[216:219], v210 offset:55296
	ds_read_b128 v[224:227], v210 offset:56320
	global_load_lds_dwordx4 v[204:205], off
	s_add_i32 m0, s54, 0x2000
	s_add_u32 s52, s52, 0x100080
	v_lshl_add_u64 v[204:205], v[220:221], 0, s[8:9]
	s_addc_u32 s53, s53, 0
	s_add_i32 s54, s91, s31
	global_load_lds_dwordx4 v[204:205], off
	v_lshl_add_u64 v[204:205], s[52:53], 0, v[182:183]
	s_mov_b32 m0, s54
	s_nop 0
	global_load_lds_dwordx4 v[204:205], off
	v_lshl_add_u64 v[204:205], s[52:53], 0, v[178:179]
	s_add_i32 m0, s54, 0x2000
	s_nop 0
	global_load_lds_dwordx4 v[204:205], off
	v_lshl_add_u64 v[204:205], v[228:229], 0, s[8:9]
	s_mov_b32 m0, s62
	s_nop 0
	global_load_lds_dwordx4 v[204:205], off
	v_lshl_add_u64 v[204:205], v[230:231], 0, s[8:9]
	s_mov_b32 m0, s63
	s_nop 0
	global_load_lds_dwordx4 v[204:205], off
	s_waitcnt vmcnt(8)
	s_waitcnt lgkmcnt(0)
	s_nop 0
	s_setprio 1
	s_barrier
	v_mfma_f32_16x16x32_bf16 v[62:65], v[130:133], v[162:165], v[62:65]
	v_mfma_f32_16x16x32_bf16 v[58:61], v[138:141], v[162:165], v[58:61]
	v_mfma_f32_16x16x32_bf16 v[50:53], v[130:133], v[170:173], v[50:53]
	v_mfma_f32_16x16x32_bf16 v[42:45], v[138:141], v[170:173], v[42:45]
	v_mfma_f32_16x16x32_bf16 v[34:37], v[130:133], v[200:203], v[34:37]
	v_mfma_f32_16x16x32_bf16 v[26:29], v[138:141], v[200:203], v[26:29]
	v_mfma_f32_16x16x32_bf16 v[18:21], v[130:133], v[216:219], v[18:21]
	v_mfma_f32_16x16x32_bf16 v[10:13], v[138:141], v[216:219], v[10:13]
	v_mfma_f32_16x16x32_bf16 v[62:65], v[134:137], v[166:169], v[62:65]
	v_mfma_f32_16x16x32_bf16 v[58:61], v[142:145], v[166:169], v[58:61]
	v_mfma_f32_16x16x32_bf16 v[50:53], v[134:137], v[174:177], v[50:53]
	v_mfma_f32_16x16x32_bf16 v[42:45], v[142:145], v[174:177], v[42:45]
	v_mfma_f32_16x16x32_bf16 v[34:37], v[134:137], v[212:215], v[34:37]
	v_mfma_f32_16x16x32_bf16 v[26:29], v[142:145], v[212:215], v[26:29]
	v_mfma_f32_16x16x32_bf16 v[18:21], v[134:137], v[224:227], v[18:21]
	v_mfma_f32_16x16x32_bf16 v[10:13], v[142:145], v[224:227], v[10:13]
	v_mfma_f32_16x16x32_bf16 v[54:57], v[146:149], v[162:165], v[54:57]
	v_mfma_f32_16x16x32_bf16 v[46:49], v[154:157], v[162:165], v[46:49]
	v_mfma_f32_16x16x32_bf16 v[38:41], v[146:149], v[170:173], v[38:41]
	v_mfma_f32_16x16x32_bf16 v[30:33], v[154:157], v[170:173], v[30:33]
	v_mfma_f32_16x16x32_bf16 v[22:25], v[146:149], v[200:203], v[22:25]
	v_mfma_f32_16x16x32_bf16 v[14:17], v[154:157], v[200:203], v[14:17]
	v_mfma_f32_16x16x32_bf16 v[6:9], v[146:149], v[216:219], v[6:9]
	v_mfma_f32_16x16x32_bf16 v[2:5], v[154:157], v[216:219], v[2:5]
	v_mfma_f32_16x16x32_bf16 v[54:57], v[150:153], v[166:169], v[54:57]
	v_mfma_f32_16x16x32_bf16 v[46:49], v[158:161], v[166:169], v[46:49]
	v_mfma_f32_16x16x32_bf16 v[38:41], v[150:153], v[174:177], v[38:41]
	v_mfma_f32_16x16x32_bf16 v[30:33], v[158:161], v[174:177], v[30:33]
	v_mfma_f32_16x16x32_bf16 v[22:25], v[150:153], v[212:215], v[22:25]
	v_mfma_f32_16x16x32_bf16 v[14:17], v[158:161], v[212:215], v[14:17]
	v_mfma_f32_16x16x32_bf16 v[6:9], v[150:153], v[224:227], v[6:9]
	v_mfma_f32_16x16x32_bf16 v[2:5], v[158:161], v[224:227], v[2:5]
	s_barrier
	s_setprio 0
	s_add_i32 s89, s89, 2
	s_add_u32 s50, s50, 0x100
	s_addc_u32 s51, s51, 0
	s_add_u32 s87, s87, 0x100
	s_addc_u32 s88, s88, 0
	s_cmp_gt_u32 s89, 61
	s_cbranch_scc0 .LBB0_224
	s_and_b64 vcc, exec, s[10:11]
	s_cbranch_vccz .LBB0_229
	s_barrier
	v_lshl_add_u32 v200, s0, 8, v1
	s_cmp_gt_i32 s84, 15
	s_mov_b64 s[50:51], -1
	s_cbranch_scc1 .LBB0_230

.Lpeelb:
	v_add_u32_e32 v142, s51, v220
	v_add_u32_e32 v158, s81, v220
	ds_read_b128 v[130:133], v142
	ds_read_b128 v[134:137], v142 offset:1024
	ds_read_b128 v[138:141], v142 offset:2048
	ds_read_b128 v[142:145], v142 offset:3072
	ds_read_b128 v[146:149], v158
	ds_read_b128 v[150:153], v158 offset:1024
	ds_read_b128 v[154:157], v158 offset:2048
	ds_read_b128 v[158:161], v158 offset:3072
	s_add_u32 s16, s0, 0xfff00080
	s_addc_u32 s17, s1, -1
	s_cmp_eq_u32 s26, 60
	s_cselect_b32 s19, s20, s17
	s_cselect_b32 s18, s21, s16
	s_cselect_b32 s17, s22, s25
	s_cselect_b32 s16, s23, s24
	v_lshl_add_u64 v[218:219], s[0:1], 0, v[194:195]
	s_add_i32 m0, s31, 0xc000
	ds_read_b128 v[162:165], v233
	ds_read_b128 v[166:169], v233 offset:1024
	ds_read_b128 v[170:173], v233 offset:2048
	ds_read_b128 v[174:177], v233 offset:3072
	ds_read_b128 v[202:205], v233 offset:4096
	ds_read_b128 v[206:209], v233 offset:5120
	ds_read_b128 v[210:213], v233 offset:6144
	ds_read_b128 v[214:217], v233 offset:7168
	global_load_lds_dwordx4 v[218:219], off
	v_lshl_add_u64 v[218:219], s[0:1], 0, v[196:197]
	s_add_i32 m0, s31, 0xe000
	s_nop 0
	global_load_lds_dwordx4 v[218:219], off
	s_waitcnt vmcnt(8)
	s_waitcnt lgkmcnt(0)
	s_nop 0
	s_setprio 1
	s_barrier
	v_mfma_f32_16x16x32_bf16 v[90:93], v[130:133], v[162:165], 0
	v_mfma_f32_16x16x32_bf16 v[58:61], v[138:141], v[162:165], 0
	v_mfma_f32_16x16x32_bf16 v[98:101], v[130:133], v[170:173], 0
	v_mfma_f32_16x16x32_bf16 v[66:69], v[138:141], v[170:173], 0
	v_mfma_f32_16x16x32_bf16 v[102:105], v[130:133], v[202:205], 0
	v_mfma_f32_16x16x32_bf16 v[70:73], v[138:141], v[202:205], 0
	v_mfma_f32_16x16x32_bf16 v[110:113], v[130:133], v[210:213], 0
	v_mfma_f32_16x16x32_bf16 v[78:81], v[138:141], v[210:213], 0
	v_mfma_f32_16x16x32_bf16 v[90:93], v[134:137], v[166:169], v[90:93]
	v_mfma_f32_16x16x32_bf16 v[58:61], v[142:145], v[166:169], v[58:61]
	v_mfma_f32_16x16x32_bf16 v[98:101], v[134:137], v[174:177], v[98:101]
	v_mfma_f32_16x16x32_bf16 v[66:69], v[142:145], v[174:177], v[66:69]
	v_mfma_f32_16x16x32_bf16 v[102:105], v[134:137], v[206:209], v[102:105]
	v_mfma_f32_16x16x32_bf16 v[70:73], v[142:145], v[206:209], v[70:73]
	v_mfma_f32_16x16x32_bf16 v[110:113], v[134:137], v[214:217], v[110:113]
	v_mfma_f32_16x16x32_bf16 v[78:81], v[142:145], v[214:217], v[78:81]
	v_mfma_f32_16x16x32_bf16 v[26:29], v[146:149], v[162:165], 0
	v_mfma_f32_16x16x32_bf16 v[2:5], v[154:157], v[162:165], 0
	v_mfma_f32_16x16x32_bf16 v[34:37], v[146:149], v[170:173], 0
	v_mfma_f32_16x16x32_bf16 v[6:9], v[154:157], v[170:173], 0
	v_mfma_f32_16x16x32_bf16 v[38:41], v[146:149], v[202:205], 0
	v_mfma_f32_16x16x32_bf16 v[10:13], v[154:157], v[202:205], 0
	v_mfma_f32_16x16x32_bf16 v[46:49], v[146:149], v[210:213], 0
	v_mfma_f32_16x16x32_bf16 v[14:17], v[154:157], v[210:213], 0
	v_mfma_f32_16x16x32_bf16 v[26:29], v[150:153], v[166:169], v[26:29]
	v_mfma_f32_16x16x32_bf16 v[2:5], v[158:161], v[166:169], v[2:5]
	v_mfma_f32_16x16x32_bf16 v[34:37], v[150:153], v[174:177], v[34:37]
	v_mfma_f32_16x16x32_bf16 v[6:9], v[158:161], v[174:177], v[6:9]
	v_mfma_f32_16x16x32_bf16 v[38:41], v[150:153], v[206:209], v[38:41]
	v_mfma_f32_16x16x32_bf16 v[10:13], v[158:161], v[206:209], v[10:13]
	v_mfma_f32_16x16x32_bf16 v[46:49], v[150:153], v[214:217], v[46:49]
	v_mfma_f32_16x16x32_bf16 v[14:17], v[158:161], v[214:217], v[14:17]
	s_barrier
	s_setprio 0
	s_add_i32 s27, s51, s15
	v_lshl_add_u64 v[218:219], s[16:17], 0, v[178:179]
	s_mov_b32 m0, s27
	ds_read_b128 v[162:165], v233 offset:16384
	ds_read_b128 v[166:169], v233 offset:17408
	ds_read_b128 v[170:173], v233 offset:18432
	ds_read_b128 v[174:177], v233 offset:19456
	ds_read_b128 v[202:205], v233 offset:20480
	ds_read_b128 v[206:209], v233 offset:21504
	ds_read_b128 v[210:213], v233 offset:22528
	ds_read_b128 v[214:217], v233 offset:23552
	global_load_lds_dwordx4 v[218:219], off
	s_add_i32 m0, s27, 0x2000
	s_add_u32 s62, s16, 0x100000
	v_lshl_add_u64 v[242:243], s[16:17], 0, v[180:181]
	s_addc_u32 s63, s17, 0
	s_add_i32 s27, s81, s15
	global_load_lds_dwordx4 v[242:243], off
	v_lshl_add_u64 v[244:245], s[62:63], 0, v[178:179]
	s_mov_b32 m0, s27
	v_lshl_add_u64 v[246:247], s[18:19], 0, v[180:181]
	global_load_lds_dwordx4 v[244:245], off
	v_lshl_add_u64 v[244:245], s[62:63], 0, v[180:181]
	s_add_i32 m0, s27, 0x2000
	s_nop 0
	global_load_lds_dwordx4 v[244:245], off
	v_lshl_add_u64 v[244:245], s[18:19], 0, v[178:179]
	s_mov_b32 m0, s31
	s_nop 0
	global_load_lds_dwordx4 v[244:245], off
	s_mov_b32 m0, s34
	s_nop 0
	global_load_lds_dwordx4 v[246:247], off
	s_waitcnt vmcnt(8)
	s_waitcnt lgkmcnt(0)
	s_setprio 1
	s_barrier
	v_mfma_f32_16x16x32_bf16 v[114:117], v[130:133], v[162:165], 0
	v_mfma_f32_16x16x32_bf16 v[82:85], v[138:141], v[162:165], 0
	v_mfma_f32_16x16x32_bf16 v[118:121], v[130:133], v[170:173], 0
	v_mfma_f32_16x16x32_bf16 v[86:89], v[138:141], v[170:173], 0
	v_mfma_f32_16x16x32_bf16 v[122:125], v[130:133], v[202:205], 0
	v_mfma_f32_16x16x32_bf16 v[94:97], v[138:141], v[202:205], 0
	v_mfma_f32_16x16x32_bf16 v[126:129], v[130:133], v[210:213], 0
	v_mfma_f32_16x16x32_bf16 v[106:109], v[138:141], v[210:213], 0
	v_mfma_f32_16x16x32_bf16 v[114:117], v[134:137], v[166:169], v[114:117]
	v_mfma_f32_16x16x32_bf16 v[82:85], v[142:145], v[166:169], v[82:85]
	v_mfma_f32_16x16x32_bf16 v[118:121], v[134:137], v[174:177], v[118:121]
	v_mfma_f32_16x16x32_bf16 v[86:89], v[142:145], v[174:177], v[86:89]
	v_mfma_f32_16x16x32_bf16 v[122:125], v[134:137], v[206:209], v[122:125]
	v_mfma_f32_16x16x32_bf16 v[94:97], v[142:145], v[206:209], v[94:97]
	v_mfma_f32_16x16x32_bf16 v[126:129], v[134:137], v[214:217], v[126:129]
	v_mfma_f32_16x16x32_bf16 v[106:109], v[142:145], v[214:217], v[106:109]
	v_mfma_f32_16x16x32_bf16 v[50:53], v[146:149], v[162:165], 0
	v_mfma_f32_16x16x32_bf16 v[18:21], v[154:157], v[162:165], 0
	v_mfma_f32_16x16x32_bf16 v[54:57], v[146:149], v[170:173], 0
	v_mfma_f32_16x16x32_bf16 v[22:25], v[154:157], v[170:173], 0
	v_mfma_f32_16x16x32_bf16 v[62:65], v[146:149], v[202:205], 0
	v_mfma_f32_16x16x32_bf16 v[30:33], v[154:157], v[202:205], 0
	v_mfma_f32_16x16x32_bf16 v[74:77], v[146:149], v[210:213], 0
	v_mfma_f32_16x16x32_bf16 v[42:45], v[154:157], v[210:213], 0
	v_mfma_f32_16x16x32_bf16 v[50:53], v[150:153], v[166:169], v[50:53]
	v_mfma_f32_16x16x32_bf16 v[18:21], v[158:161], v[166:169], v[18:21]
	v_mfma_f32_16x16x32_bf16 v[54:57], v[150:153], v[174:177], v[54:57]
	v_mfma_f32_16x16x32_bf16 v[22:25], v[158:161], v[174:177], v[22:25]
	v_mfma_f32_16x16x32_bf16 v[62:65], v[150:153], v[206:209], v[62:65]
	v_mfma_f32_16x16x32_bf16 v[30:33], v[158:161], v[206:209], v[30:33]
	v_mfma_f32_16x16x32_bf16 v[74:77], v[150:153], v[214:217], v[74:77]
	v_mfma_f32_16x16x32_bf16 v[42:45], v[158:161], v[214:217], v[42:45]
	s_barrier
	s_setprio 0
	s_add_i32 s27, 0, 0x18000
	s_add_i32 s59, 0, 0x1c000
	v_add_u32_e32 v142, s27, v220
	v_add_u32_e32 v158, s59, v220
	ds_read_b128 v[130:133], v142
	ds_read_b128 v[134:137], v142 offset:1024
	ds_read_b128 v[138:141], v142 offset:2048
	ds_read_b128 v[142:145], v142 offset:3072
	ds_read_b128 v[146:149], v158
	ds_read_b128 v[150:153], v158 offset:1024
	ds_read_b128 v[154:157], v158 offset:2048
	ds_read_b128 v[158:161], v158 offset:3072
	s_add_u32 s18, s18, 0x100000
	s_addc_u32 s19, s19, 0
	s_mov_b32 m0, s35
	v_lshl_add_u64 v[248:249], s[18:19], 0, v[178:179]
	ds_read_b128 v[162:165], v233 offset:32768
	ds_read_b128 v[166:169], v233 offset:33792
	ds_read_b128 v[170:173], v233 offset:34816
	ds_read_b128 v[174:177], v233 offset:35840
	ds_read_b128 v[202:205], v233 offset:36864
	ds_read_b128 v[206:209], v233 offset:37888
	ds_read_b128 v[210:213], v233 offset:38912
	ds_read_b128 v[214:217], v233 offset:39936
	global_load_lds_dwordx4 v[248:249], off
	v_lshl_add_u64 v[248:249], s[18:19], 0, v[180:181]
	s_mov_b32 m0, s86
	s_nop 0
	global_load_lds_dwordx4 v[248:249], off
	s_waitcnt vmcnt(8)
	s_waitcnt lgkmcnt(0)
	s_setprio 1
	s_barrier
	v_mfma_f32_16x16x32_bf16 v[90:93], v[130:133], v[162:165], v[90:93]
	v_mfma_f32_16x16x32_bf16 v[58:61], v[138:141], v[162:165], v[58:61]
	v_mfma_f32_16x16x32_bf16 v[98:101], v[130:133], v[170:173], v[98:101]
	v_mfma_f32_16x16x32_bf16 v[66:69], v[138:141], v[170:173], v[66:69]
	v_mfma_f32_16x16x32_bf16 v[102:105], v[130:133], v[202:205], v[102:105]
	v_mfma_f32_16x16x32_bf16 v[70:73], v[138:141], v[202:205], v[70:73]
	v_mfma_f32_16x16x32_bf16 v[110:113], v[130:133], v[210:213], v[110:113]
	v_mfma_f32_16x16x32_bf16 v[78:81], v[138:141], v[210:213], v[78:81]
	v_mfma_f32_16x16x32_bf16 v[90:93], v[134:137], v[166:169], v[90:93]
	v_mfma_f32_16x16x32_bf16 v[58:61], v[142:145], v[166:169], v[58:61]
	v_mfma_f32_16x16x32_bf16 v[98:101], v[134:137], v[174:177], v[98:101]
	v_mfma_f32_16x16x32_bf16 v[66:69], v[142:145], v[174:177], v[66:69]
	v_mfma_f32_16x16x32_bf16 v[102:105], v[134:137], v[206:209], v[102:105]
	v_mfma_f32_16x16x32_bf16 v[70:73], v[142:145], v[206:209], v[70:73]
	v_mfma_f32_16x16x32_bf16 v[110:113], v[134:137], v[214:217], v[110:113]
	v_mfma_f32_16x16x32_bf16 v[78:81], v[142:145], v[214:217], v[78:81]
	v_mfma_f32_16x16x32_bf16 v[26:29], v[146:149], v[162:165], v[26:29]
	v_mfma_f32_16x16x32_bf16 v[2:5], v[154:157], v[162:165], v[2:5]
	v_mfma_f32_16x16x32_bf16 v[34:37], v[146:149], v[170:173], v[34:37]
	v_mfma_f32_16x16x32_bf16 v[6:9], v[154:157], v[170:173], v[6:9]
	v_mfma_f32_16x16x32_bf16 v[38:41], v[146:149], v[202:205], v[38:41]
	v_mfma_f32_16x16x32_bf16 v[10:13], v[154:157], v[202:205], v[10:13]
	v_mfma_f32_16x16x32_bf16 v[46:49], v[146:149], v[210:213], v[46:49]
	v_mfma_f32_16x16x32_bf16 v[14:17], v[154:157], v[210:213], v[14:17]
	v_mfma_f32_16x16x32_bf16 v[26:29], v[150:153], v[166:169], v[26:29]
	v_mfma_f32_16x16x32_bf16 v[2:5], v[158:161], v[166:169], v[2:5]
	v_mfma_f32_16x16x32_bf16 v[34:37], v[150:153], v[174:177], v[34:37]
	v_mfma_f32_16x16x32_bf16 v[6:9], v[158:161], v[174:177], v[6:9]
	v_mfma_f32_16x16x32_bf16 v[38:41], v[150:153], v[206:209], v[38:41]
	v_mfma_f32_16x16x32_bf16 v[10:13], v[158:161], v[206:209], v[10:13]
	v_mfma_f32_16x16x32_bf16 v[46:49], v[150:153], v[214:217], v[46:49]
	v_mfma_f32_16x16x32_bf16 v[14:17], v[158:161], v[214:217], v[14:17]
	s_barrier
	s_setprio 0
	s_add_i32 s18, s27, s15
	v_lshl_add_u64 v[218:219], v[218:219], 0, s[44:45]
	s_mov_b32 m0, s18
	ds_read_b128 v[162:165], v233 offset:49152
	ds_read_b128 v[166:169], v233 offset:50176
	ds_read_b128 v[170:173], v233 offset:51200
	ds_read_b128 v[174:177], v233 offset:52224
	ds_read_b128 v[202:205], v233 offset:53248
	ds_read_b128 v[206:209], v233 offset:54272
	ds_read_b128 v[210:213], v233 offset:55296
	ds_read_b128 v[214:217], v233 offset:56320
	global_load_lds_dwordx4 v[218:219], off
	s_add_i32 m0, s18, 0x2000
	s_add_u32 s16, s16, 0x100080
	v_lshl_add_u64 v[218:219], v[242:243], 0, s[44:45]
	s_addc_u32 s17, s17, 0
	s_add_i32 s18, s59, s15
	global_load_lds_dwordx4 v[218:219], off
	v_lshl_add_u64 v[218:219], s[16:17], 0, v[178:179]
	s_mov_b32 m0, s18
	s_nop 0
	global_load_lds_dwordx4 v[218:219], off
	v_lshl_add_u64 v[218:219], s[16:17], 0, v[180:181]
	s_add_i32 m0, s18, 0x2000
	s_nop 0
	global_load_lds_dwordx4 v[218:219], off
	v_lshl_add_u64 v[218:219], v[244:245], 0, s[44:45]
	s_mov_b32 m0, s66
	s_nop 0
	global_load_lds_dwordx4 v[218:219], off
	v_lshl_add_u64 v[218:219], v[246:247], 0, s[44:45]
	s_mov_b32 m0, s67
	s_nop 0
	global_load_lds_dwordx4 v[218:219], off
	s_waitcnt vmcnt(8)
	s_waitcnt lgkmcnt(0)
	s_nop 0
	s_setprio 1
	s_barrier
	v_mfma_f32_16x16x32_bf16 v[114:117], v[130:133], v[162:165], v[114:117]
	v_mfma_f32_16x16x32_bf16 v[82:85], v[138:141], v[162:165], v[82:85]
	v_mfma_f32_16x16x32_bf16 v[118:121], v[130:133], v[170:173], v[118:121]
	v_mfma_f32_16x16x32_bf16 v[86:89], v[138:141], v[170:173], v[86:89]
	v_mfma_f32_16x16x32_bf16 v[122:125], v[130:133], v[202:205], v[122:125]
	v_mfma_f32_16x16x32_bf16 v[94:97], v[138:141], v[202:205], v[94:97]
	v_mfma_f32_16x16x32_bf16 v[126:129], v[130:133], v[210:213], v[126:129]
	v_mfma_f32_16x16x32_bf16 v[106:109], v[138:141], v[210:213], v[106:109]
	v_mfma_f32_16x16x32_bf16 v[114:117], v[134:137], v[166:169], v[114:117]
	v_mfma_f32_16x16x32_bf16 v[82:85], v[142:145], v[166:169], v[82:85]
	v_mfma_f32_16x16x32_bf16 v[118:121], v[134:137], v[174:177], v[118:121]
	v_mfma_f32_16x16x32_bf16 v[86:89], v[142:145], v[174:177], v[86:89]
	v_mfma_f32_16x16x32_bf16 v[122:125], v[134:137], v[206:209], v[122:125]
	v_mfma_f32_16x16x32_bf16 v[94:97], v[142:145], v[206:209], v[94:97]
	v_mfma_f32_16x16x32_bf16 v[126:129], v[134:137], v[214:217], v[126:129]
	v_mfma_f32_16x16x32_bf16 v[106:109], v[142:145], v[214:217], v[106:109]
	v_mfma_f32_16x16x32_bf16 v[50:53], v[146:149], v[162:165], v[50:53]
	v_mfma_f32_16x16x32_bf16 v[18:21], v[154:157], v[162:165], v[18:21]
	v_mfma_f32_16x16x32_bf16 v[54:57], v[146:149], v[170:173], v[54:57]
	v_mfma_f32_16x16x32_bf16 v[22:25], v[154:157], v[170:173], v[22:25]
	v_mfma_f32_16x16x32_bf16 v[62:65], v[146:149], v[202:205], v[62:65]
	v_mfma_f32_16x16x32_bf16 v[30:33], v[154:157], v[202:205], v[30:33]
	v_mfma_f32_16x16x32_bf16 v[74:77], v[146:149], v[210:213], v[74:77]
	v_mfma_f32_16x16x32_bf16 v[42:45], v[154:157], v[210:213], v[42:45]
	v_mfma_f32_16x16x32_bf16 v[50:53], v[150:153], v[166:169], v[50:53]
	v_mfma_f32_16x16x32_bf16 v[18:21], v[158:161], v[166:169], v[18:21]
	v_mfma_f32_16x16x32_bf16 v[54:57], v[150:153], v[174:177], v[54:57]
	v_mfma_f32_16x16x32_bf16 v[22:25], v[158:161], v[174:177], v[22:25]
	v_mfma_f32_16x16x32_bf16 v[62:65], v[150:153], v[206:209], v[62:65]
	v_mfma_f32_16x16x32_bf16 v[30:33], v[158:161], v[206:209], v[30:33]
	v_mfma_f32_16x16x32_bf16 v[74:77], v[150:153], v[214:217], v[74:77]
	v_mfma_f32_16x16x32_bf16 v[42:45], v[158:161], v[214:217], v[42:45]
	s_barrier
	s_setprio 0
	s_add_i32 s26, s26, 2
	s_add_u32 s0, s0, 0x100
	s_addc_u32 s1, s1, 0
	s_add_u32 s24, s24, 0x100
	s_addc_u32 s25, s25, 0
.LBB0_672:
	v_add_u32_e32 v142, s51, v220
	v_add_u32_e32 v158, s81, v220
	ds_read_b128 v[130:133], v142
	ds_read_b128 v[134:137], v142 offset:1024
	ds_read_b128 v[138:141], v142 offset:2048
	ds_read_b128 v[142:145], v142 offset:3072
	ds_read_b128 v[146:149], v158
	ds_read_b128 v[150:153], v158 offset:1024
	ds_read_b128 v[154:157], v158 offset:2048
	ds_read_b128 v[158:161], v158 offset:3072
	s_add_u32 s16, s0, 0xfff00080
	s_addc_u32 s17, s1, -1
	s_cmp_eq_u32 s26, 60
	s_cselect_b32 s19, s20, s17
	s_cselect_b32 s18, s21, s16
	s_cselect_b32 s17, s22, s25
	s_cselect_b32 s16, s23, s24
	v_lshl_add_u64 v[218:219], s[0:1], 0, v[194:195]
	s_add_i32 m0, s31, 0xc000
	ds_read_b128 v[162:165], v233
	ds_read_b128 v[166:169], v233 offset:1024
	ds_read_b128 v[170:173], v233 offset:2048
	ds_read_b128 v[174:177], v233 offset:3072
	ds_read_b128 v[202:205], v233 offset:4096
	ds_read_b128 v[206:209], v233 offset:5120
	ds_read_b128 v[210:213], v233 offset:6144
	ds_read_b128 v[214:217], v233 offset:7168
	global_load_lds_dwordx4 v[218:219], off
	v_lshl_add_u64 v[218:219], s[0:1], 0, v[196:197]
	s_add_i32 m0, s31, 0xe000
	s_nop 0
	global_load_lds_dwordx4 v[218:219], off
	s_waitcnt vmcnt(8)
	s_waitcnt lgkmcnt(0)
	s_setprio 1
	s_barrier
	v_mfma_f32_16x16x32_bf16 v[90:93], v[130:133], v[162:165], v[90:93]
	v_mfma_f32_16x16x32_bf16 v[58:61], v[138:141], v[162:165], v[58:61]
	v_mfma_f32_16x16x32_bf16 v[98:101], v[130:133], v[170:173], v[98:101]
	v_mfma_f32_16x16x32_bf16 v[66:69], v[138:141], v[170:173], v[66:69]
	v_mfma_f32_16x16x32_bf16 v[102:105], v[130:133], v[202:205], v[102:105]
	v_mfma_f32_16x16x32_bf16 v[70:73], v[138:141], v[202:205], v[70:73]
	v_mfma_f32_16x16x32_bf16 v[110:113], v[130:133], v[210:213], v[110:113]
	v_mfma_f32_16x16x32_bf16 v[78:81], v[138:141], v[210:213], v[78:81]
	v_mfma_f32_16x16x32_bf16 v[90:93], v[134:137], v[166:169], v[90:93]
	v_mfma_f32_16x16x32_bf16 v[58:61], v[142:145], v[166:169], v[58:61]
	v_mfma_f32_16x16x32_bf16 v[98:101], v[134:137], v[174:177], v[98:101]
	v_mfma_f32_16x16x32_bf16 v[66:69], v[142:145], v[174:177], v[66:69]
	v_mfma_f32_16x16x32_bf16 v[102:105], v[134:137], v[206:209], v[102:105]
	v_mfma_f32_16x16x32_bf16 v[70:73], v[142:145], v[206:209], v[70:73]
	v_mfma_f32_16x16x32_bf16 v[110:113], v[134:137], v[214:217], v[110:113]
	v_mfma_f32_16x16x32_bf16 v[78:81], v[142:145], v[214:217], v[78:81]
	v_mfma_f32_16x16x32_bf16 v[26:29], v[146:149], v[162:165], v[26:29]
	v_mfma_f32_16x16x32_bf16 v[2:5], v[154:157], v[162:165], v[2:5]
	v_mfma_f32_16x16x32_bf16 v[34:37], v[146:149], v[170:173], v[34:37]
	v_mfma_f32_16x16x32_bf16 v[6:9], v[154:157], v[170:173], v[6:9]
	v_mfma_f32_16x16x32_bf16 v[38:41], v[146:149], v[202:205], v[38:41]
	v_mfma_f32_16x16x32_bf16 v[10:13], v[154:157], v[202:205], v[10:13]
	v_mfma_f32_16x16x32_bf16 v[46:49], v[146:149], v[210:213], v[46:49]
	v_mfma_f32_16x16x32_bf16 v[14:17], v[154:157], v[210:213], v[14:17]
	v_mfma_f32_16x16x32_bf16 v[26:29], v[150:153], v[166:169], v[26:29]
	v_mfma_f32_16x16x32_bf16 v[2:5], v[158:161], v[166:169], v[2:5]
	v_mfma_f32_16x16x32_bf16 v[34:37], v[150:153], v[174:177], v[34:37]
	v_mfma_f32_16x16x32_bf16 v[6:9], v[158:161], v[174:177], v[6:9]
	v_mfma_f32_16x16x32_bf16 v[38:41], v[150:153], v[206:209], v[38:41]
	v_mfma_f32_16x16x32_bf16 v[10:13], v[158:161], v[206:209], v[10:13]
	v_mfma_f32_16x16x32_bf16 v[46:49], v[150:153], v[214:217], v[46:49]
	v_mfma_f32_16x16x32_bf16 v[14:17], v[158:161], v[214:217], v[14:17]
	s_barrier
	s_setprio 0
	s_add_i32 s27, s51, s15
	v_lshl_add_u64 v[218:219], s[16:17], 0, v[178:179]
	s_mov_b32 m0, s27
	ds_read_b128 v[162:165], v233 offset:16384
	ds_read_b128 v[166:169], v233 offset:17408
	ds_read_b128 v[170:173], v233 offset:18432
	ds_read_b128 v[174:177], v233 offset:19456
	ds_read_b128 v[202:205], v233 offset:20480
	ds_read_b128 v[206:209], v233 offset:21504
	ds_read_b128 v[210:213], v233 offset:22528
	ds_read_b128 v[214:217], v233 offset:23552
	global_load_lds_dwordx4 v[218:219], off
	s_add_i32 m0, s27, 0x2000
	s_add_u32 s62, s16, 0x100000
	v_lshl_add_u64 v[242:243], s[16:17], 0, v[180:181]
	s_addc_u32 s63, s17, 0
	s_add_i32 s27, s81, s15
	global_load_lds_dwordx4 v[242:243], off
	v_lshl_add_u64 v[244:245], s[62:63], 0, v[178:179]
	s_mov_b32 m0, s27
	v_lshl_add_u64 v[246:247], s[18:19], 0, v[180:181]
	global_load_lds_dwordx4 v[244:245], off
	v_lshl_add_u64 v[244:245], s[62:63], 0, v[180:181]
	s_add_i32 m0, s27, 0x2000
	s_nop 0
	global_load_lds_dwordx4 v[244:245], off
	v_lshl_add_u64 v[244:245], s[18:19], 0, v[178:179]
	s_mov_b32 m0, s31
	s_nop 0
	global_load_lds_dwordx4 v[244:245], off
	s_mov_b32 m0, s34
	s_nop 0
	global_load_lds_dwordx4 v[246:247], off
	s_waitcnt vmcnt(8)
	s_waitcnt lgkmcnt(0)
	s_setprio 1
	s_barrier
	v_mfma_f32_16x16x32_bf16 v[114:117], v[130:133], v[162:165], v[114:117]
	v_mfma_f32_16x16x32_bf16 v[82:85], v[138:141], v[162:165], v[82:85]
	v_mfma_f32_16x16x32_bf16 v[118:121], v[130:133], v[170:173], v[118:121]
	v_mfma_f32_16x16x32_bf16 v[86:89], v[138:141], v[170:173], v[86:89]
	v_mfma_f32_16x16x32_bf16 v[122:125], v[130:133], v[202:205], v[122:125]
	v_mfma_f32_16x16x32_bf16 v[94:97], v[138:141], v[202:205], v[94:97]
	v_mfma_f32_16x16x32_bf16 v[126:129], v[130:133], v[210:213], v[126:129]
	v_mfma_f32_16x16x32_bf16 v[106:109], v[138:141], v[210:213], v[106:109]
	v_mfma_f32_16x16x32_bf16 v[114:117], v[134:137], v[166:169], v[114:117]
	v_mfma_f32_16x16x32_bf16 v[82:85], v[142:145], v[166:169], v[82:85]
	v_mfma_f32_16x16x32_bf16 v[118:121], v[134:137], v[174:177], v[118:121]
	v_mfma_f32_16x16x32_bf16 v[86:89], v[142:145], v[174:177], v[86:89]
	v_mfma_f32_16x16x32_bf16 v[122:125], v[134:137], v[206:209], v[122:125]
	v_mfma_f32_16x16x32_bf16 v[94:97], v[142:145], v[206:209], v[94:97]
	v_mfma_f32_16x16x32_bf16 v[126:129], v[134:137], v[214:217], v[126:129]
	v_mfma_f32_16x16x32_bf16 v[106:109], v[142:145], v[214:217], v[106:109]
	v_mfma_f32_16x16x32_bf16 v[50:53], v[146:149], v[162:165], v[50:53]
	v_mfma_f32_16x16x32_bf16 v[18:21], v[154:157], v[162:165], v[18:21]
	v_mfma_f32_16x16x32_bf16 v[54:57], v[146:149], v[170:173], v[54:57]
	v_mfma_f32_16x16x32_bf16 v[22:25], v[154:157], v[170:173], v[22:25]
	v_mfma_f32_16x16x32_bf16 v[62:65], v[146:149], v[202:205], v[62:65]
	v_mfma_f32_16x16x32_bf16 v[30:33], v[154:157], v[202:205], v[30:33]
	v_mfma_f32_16x16x32_bf16 v[74:77], v[146:149], v[210:213], v[74:77]
	v_mfma_f32_16x16x32_bf16 v[42:45], v[154:157], v[210:213], v[42:45]
	v_mfma_f32_16x16x32_bf16 v[50:53], v[150:153], v[166:169], v[50:53]
	v_mfma_f32_16x16x32_bf16 v[18:21], v[158:161], v[166:169], v[18:21]
	v_mfma_f32_16x16x32_bf16 v[54:57], v[150:153], v[174:177], v[54:57]
	v_mfma_f32_16x16x32_bf16 v[22:25], v[158:161], v[174:177], v[22:25]
	v_mfma_f32_16x16x32_bf16 v[62:65], v[150:153], v[206:209], v[62:65]
	v_mfma_f32_16x16x32_bf16 v[30:33], v[158:161], v[206:209], v[30:33]
	v_mfma_f32_16x16x32_bf16 v[74:77], v[150:153], v[214:217], v[74:77]
	v_mfma_f32_16x16x32_bf16 v[42:45], v[158:161], v[214:217], v[42:45]
	s_barrier
	s_setprio 0
	s_add_i32 s27, 0, 0x18000
	s_add_i32 s59, 0, 0x1c000
	v_add_u32_e32 v142, s27, v220
	v_add_u32_e32 v158, s59, v220
	ds_read_b128 v[130:133], v142
	ds_read_b128 v[134:137], v142 offset:1024
	ds_read_b128 v[138:141], v142 offset:2048
	ds_read_b128 v[142:145], v142 offset:3072
	ds_read_b128 v[146:149], v158
	ds_read_b128 v[150:153], v158 offset:1024
	ds_read_b128 v[154:157], v158 offset:2048
	ds_read_b128 v[158:161], v158 offset:3072
	s_add_u32 s18, s18, 0x100000
	s_addc_u32 s19, s19, 0
	s_mov_b32 m0, s35
	v_lshl_add_u64 v[248:249], s[18:19], 0, v[178:179]
	ds_read_b128 v[162:165], v233 offset:32768
	ds_read_b128 v[166:169], v233 offset:33792
	ds_read_b128 v[170:173], v233 offset:34816
	ds_read_b128 v[174:177], v233 offset:35840
	ds_read_b128 v[202:205], v233 offset:36864
	ds_read_b128 v[206:209], v233 offset:37888
	ds_read_b128 v[210:213], v233 offset:38912
	ds_read_b128 v[214:217], v233 offset:39936
	global_load_lds_dwordx4 v[248:249], off
	v_lshl_add_u64 v[248:249], s[18:19], 0, v[180:181]
	s_mov_b32 m0, s86
	s_nop 0
	global_load_lds_dwordx4 v[248:249], off
	s_waitcnt vmcnt(8)
	s_waitcnt lgkmcnt(0)
	s_setprio 1
	s_barrier
	v_mfma_f32_16x16x32_bf16 v[90:93], v[130:133], v[162:165], v[90:93]
	v_mfma_f32_16x16x32_bf16 v[58:61], v[138:141], v[162:165], v[58:61]
	v_mfma_f32_16x16x32_bf16 v[98:101], v[130:133], v[170:173], v[98:101]
	v_mfma_f32_16x16x32_bf16 v[66:69], v[138:141], v[170:173], v[66:69]
	v_mfma_f32_16x16x32_bf16 v[102:105], v[130:133], v[202:205], v[102:105]
	v_mfma_f32_16x16x32_bf16 v[70:73], v[138:141], v[202:205], v[70:73]
	v_mfma_f32_16x16x32_bf16 v[110:113], v[130:133], v[210:213], v[110:113]
	v_mfma_f32_16x16x32_bf16 v[78:81], v[138:141], v[210:213], v[78:81]
	v_mfma_f32_16x16x32_bf16 v[90:93], v[134:137], v[166:169], v[90:93]
	v_mfma_f32_16x16x32_bf16 v[58:61], v[142:145], v[166:169], v[58:61]
	v_mfma_f32_16x16x32_bf16 v[98:101], v[134:137], v[174:177], v[98:101]
	v_mfma_f32_16x16x32_bf16 v[66:69], v[142:145], v[174:177], v[66:69]
	v_mfma_f32_16x16x32_bf16 v[102:105], v[134:137], v[206:209], v[102:105]
	v_mfma_f32_16x16x32_bf16 v[70:73], v[142:145], v[206:209], v[70:73]
	v_mfma_f32_16x16x32_bf16 v[110:113], v[134:137], v[214:217], v[110:113]
	v_mfma_f32_16x16x32_bf16 v[78:81], v[142:145], v[214:217], v[78:81]
	v_mfma_f32_16x16x32_bf16 v[26:29], v[146:149], v[162:165], v[26:29]
	v_mfma_f32_16x16x32_bf16 v[2:5], v[154:157], v[162:165], v[2:5]
	v_mfma_f32_16x16x32_bf16 v[34:37], v[146:149], v[170:173], v[34:37]
	v_mfma_f32_16x16x32_bf16 v[6:9], v[154:157], v[170:173], v[6:9]
	v_mfma_f32_16x16x32_bf16 v[38:41], v[146:149], v[202:205], v[38:41]
	v_mfma_f32_16x16x32_bf16 v[10:13], v[154:157], v[202:205], v[10:13]
	v_mfma_f32_16x16x32_bf16 v[46:49], v[146:149], v[210:213], v[46:49]
	v_mfma_f32_16x16x32_bf16 v[14:17], v[154:157], v[210:213], v[14:17]
	v_mfma_f32_16x16x32_bf16 v[26:29], v[150:153], v[166:169], v[26:29]
	v_mfma_f32_16x16x32_bf16 v[2:5], v[158:161], v[166:169], v[2:5]
	v_mfma_f32_16x16x32_bf16 v[34:37], v[150:153], v[174:177], v[34:37]
	v_mfma_f32_16x16x32_bf16 v[6:9], v[158:161], v[174:177], v[6:9]
	v_mfma_f32_16x16x32_bf16 v[38:41], v[150:153], v[206:209], v[38:41]
	v_mfma_f32_16x16x32_bf16 v[10:13], v[158:161], v[206:209], v[10:13]
	v_mfma_f32_16x16x32_bf16 v[46:49], v[150:153], v[214:217], v[46:49]
	v_mfma_f32_16x16x32_bf16 v[14:17], v[158:161], v[214:217], v[14:17]
	s_barrier
	s_setprio 0
	s_add_i32 s18, s27, s15
	v_lshl_add_u64 v[218:219], v[218:219], 0, s[44:45]
	s_mov_b32 m0, s18
	ds_read_b128 v[162:165], v233 offset:49152
	ds_read_b128 v[166:169], v233 offset:50176
	ds_read_b128 v[170:173], v233 offset:51200
	ds_read_b128 v[174:177], v233 offset:52224
	ds_read_b128 v[202:205], v233 offset:53248
	ds_read_b128 v[206:209], v233 offset:54272
	ds_read_b128 v[210:213], v233 offset:55296
	ds_read_b128 v[214:217], v233 offset:56320
	global_load_lds_dwordx4 v[218:219], off
	s_add_i32 m0, s18, 0x2000
	s_add_u32 s16, s16, 0x100080
	v_lshl_add_u64 v[218:219], v[242:243], 0, s[44:45]
	s_addc_u32 s17, s17, 0
	s_add_i32 s18, s59, s15
	global_load_lds_dwordx4 v[218:219], off
	v_lshl_add_u64 v[218:219], s[16:17], 0, v[178:179]
	s_mov_b32 m0, s18
	s_nop 0
	global_load_lds_dwordx4 v[218:219], off
	v_lshl_add_u64 v[218:219], s[16:17], 0, v[180:181]
	s_add_i32 m0, s18, 0x2000
	s_nop 0
	global_load_lds_dwordx4 v[218:219], off
	v_lshl_add_u64 v[218:219], v[244:245], 0, s[44:45]
	s_mov_b32 m0, s66
	s_nop 0
	global_load_lds_dwordx4 v[218:219], off
	v_lshl_add_u64 v[218:219], v[246:247], 0, s[44:45]
	s_mov_b32 m0, s67
	s_nop 0
	global_load_lds_dwordx4 v[218:219], off
	s_waitcnt vmcnt(8)
	s_waitcnt lgkmcnt(0)
	s_nop 0
	s_setprio 1
	s_barrier
	v_mfma_f32_16x16x32_bf16 v[114:117], v[130:133], v[162:165], v[114:117]
	v_mfma_f32_16x16x32_bf16 v[82:85], v[138:141], v[162:165], v[82:85]
	v_mfma_f32_16x16x32_bf16 v[118:121], v[130:133], v[170:173], v[118:121]
	v_mfma_f32_16x16x32_bf16 v[86:89], v[138:141], v[170:173], v[86:89]
	v_mfma_f32_16x16x32_bf16 v[122:125], v[130:133], v[202:205], v[122:125]
	v_mfma_f32_16x16x32_bf16 v[94:97], v[138:141], v[202:205], v[94:97]
	v_mfma_f32_16x16x32_bf16 v[126:129], v[130:133], v[210:213], v[126:129]
	v_mfma_f32_16x16x32_bf16 v[106:109], v[138:141], v[210:213], v[106:109]
	v_mfma_f32_16x16x32_bf16 v[114:117], v[134:137], v[166:169], v[114:117]
	v_mfma_f32_16x16x32_bf16 v[82:85], v[142:145], v[166:169], v[82:85]
	v_mfma_f32_16x16x32_bf16 v[118:121], v[134:137], v[174:177], v[118:121]
	v_mfma_f32_16x16x32_bf16 v[86:89], v[142:145], v[174:177], v[86:89]
	v_mfma_f32_16x16x32_bf16 v[122:125], v[134:137], v[206:209], v[122:125]
	v_mfma_f32_16x16x32_bf16 v[94:97], v[142:145], v[206:209], v[94:97]
	v_mfma_f32_16x16x32_bf16 v[126:129], v[134:137], v[214:217], v[126:129]
	v_mfma_f32_16x16x32_bf16 v[106:109], v[142:145], v[214:217], v[106:109]
	v_mfma_f32_16x16x32_bf16 v[50:53], v[146:149], v[162:165], v[50:53]
	v_mfma_f32_16x16x32_bf16 v[18:21], v[154:157], v[162:165], v[18:21]
	v_mfma_f32_16x16x32_bf16 v[54:57], v[146:149], v[170:173], v[54:57]
	v_mfma_f32_16x16x32_bf16 v[22:25], v[154:157], v[170:173], v[22:25]
	v_mfma_f32_16x16x32_bf16 v[62:65], v[146:149], v[202:205], v[62:65]
	v_mfma_f32_16x16x32_bf16 v[30:33], v[154:157], v[202:205], v[30:33]
	v_mfma_f32_16x16x32_bf16 v[74:77], v[146:149], v[210:213], v[74:77]
	v_mfma_f32_16x16x32_bf16 v[42:45], v[154:157], v[210:213], v[42:45]
	v_mfma_f32_16x16x32_bf16 v[50:53], v[150:153], v[166:169], v[50:53]
	v_mfma_f32_16x16x32_bf16 v[18:21], v[158:161], v[166:169], v[18:21]
	v_mfma_f32_16x16x32_bf16 v[54:57], v[150:153], v[174:177], v[54:57]
	v_mfma_f32_16x16x32_bf16 v[22:25], v[158:161], v[174:177], v[22:25]
	v_mfma_f32_16x16x32_bf16 v[62:65], v[150:153], v[206:209], v[62:65]
	v_mfma_f32_16x16x32_bf16 v[30:33], v[158:161], v[206:209], v[30:33]
	v_mfma_f32_16x16x32_bf16 v[74:77], v[150:153], v[214:217], v[74:77]
	v_mfma_f32_16x16x32_bf16 v[42:45], v[158:161], v[214:217], v[42:45]
	s_barrier
	s_setprio 0
	s_add_i32 s26, s26, 2
	s_add_u32 s0, s0, 0x100
	s_addc_u32 s1, s1, 0
	s_add_u32 s24, s24, 0x100
	s_addc_u32 s25, s25, 0
	s_cmp_gt_u32 s26, 61
	s_cbranch_scc0 .LBB0_672
	s_and_b64 vcc, exec, s[90:91]
	s_cbranch_vccz .LBB0_675
	s_barrier

.Lpeelc:
	ds_read_b128 v[156:159], v153
	ds_read_b128 v[160:163], v153 offset:1024
	ds_read_b128 v[164:167], v153 offset:2048
	ds_read_b128 v[168:171], v153 offset:3072
	ds_read_b128 v[172:175], v154
	ds_read_b128 v[176:179], v154 offset:1024
	ds_read_b128 v[180:183], v154 offset:2048
	ds_read_b128 v[184:187], v154 offset:3072
	s_add_u32 s36, s26, 0xfff00080
	s_addc_u32 s37, s27, -1
	s_cmp_eq_u32 s54, 60
	s_cselect_b32 s39, s19, s37
	s_cselect_b32 s38, s50, s36
	s_cselect_b32 s37, s17, s53
	s_cselect_b32 s36, s51, s52
	v_lshl_add_u64 v[148:149], s[26:27], 0, v[140:141]
	s_add_i32 m0, s25, 0xc000
	ds_read_b128 v[188:191], v155
	ds_read_b128 v[192:195], v155 offset:1024
	ds_read_b128 v[196:199], v155 offset:2048
	ds_read_b128 v[200:203], v155 offset:3072
	ds_read_b128 v[204:207], v155 offset:4096
	ds_read_b128 v[208:211], v155 offset:5120
	ds_read_b128 v[212:215], v155 offset:6144
	ds_read_b128 v[216:219], v155 offset:7168
	global_load_lds_dwordx4 v[148:149], off
	v_lshl_add_u64 v[148:149], s[26:27], 0, v[142:143]
	s_add_i32 m0, s25, 0xe000
	s_nop 0
	global_load_lds_dwordx4 v[148:149], off
	s_waitcnt vmcnt(8)
	s_waitcnt lgkmcnt(0)
	s_setprio 1
	s_barrier
	v_mfma_f32_16x16x32_bf16 v[126:129], v[156:159], v[188:191], 0
	v_mfma_f32_16x16x32_bf16 v[122:125], v[164:167], v[188:191], 0
	v_mfma_f32_16x16x32_bf16 v[118:121], v[156:159], v[196:199], 0
	v_mfma_f32_16x16x32_bf16 v[114:117], v[164:167], v[196:199], 0
	v_mfma_f32_16x16x32_bf16 v[94:97], v[156:159], v[204:207], 0
	v_mfma_f32_16x16x32_bf16 v[90:93], v[164:167], v[204:207], 0
	v_mfma_f32_16x16x32_bf16 v[86:89], v[156:159], v[212:215], 0
	v_mfma_f32_16x16x32_bf16 v[82:85], v[164:167], v[212:215], 0
	v_mfma_f32_16x16x32_bf16 v[126:129], v[160:163], v[192:195], v[126:129]
	v_mfma_f32_16x16x32_bf16 v[122:125], v[168:171], v[192:195], v[122:125]
	v_mfma_f32_16x16x32_bf16 v[118:121], v[160:163], v[200:203], v[118:121]
	v_mfma_f32_16x16x32_bf16 v[114:117], v[168:171], v[200:203], v[114:117]
	v_mfma_f32_16x16x32_bf16 v[94:97], v[160:163], v[208:211], v[94:97]
	v_mfma_f32_16x16x32_bf16 v[90:93], v[168:171], v[208:211], v[90:93]
	v_mfma_f32_16x16x32_bf16 v[86:89], v[160:163], v[216:219], v[86:89]
	v_mfma_f32_16x16x32_bf16 v[82:85], v[168:171], v[216:219], v[82:85]
	v_mfma_f32_16x16x32_bf16 v[110:113], v[172:175], v[188:191], 0
	v_mfma_f32_16x16x32_bf16 v[106:109], v[180:183], v[188:191], 0
	v_mfma_f32_16x16x32_bf16 v[102:105], v[172:175], v[196:199], 0
	v_mfma_f32_16x16x32_bf16 v[98:101], v[180:183], v[196:199], 0
	v_mfma_f32_16x16x32_bf16 v[78:81], v[172:175], v[204:207], 0
	v_mfma_f32_16x16x32_bf16 v[74:77], v[180:183], v[204:207], 0
	v_mfma_f32_16x16x32_bf16 v[70:73], v[172:175], v[212:215], 0
	v_mfma_f32_16x16x32_bf16 v[66:69], v[180:183], v[212:215], 0
	v_mfma_f32_16x16x32_bf16 v[110:113], v[176:179], v[192:195], v[110:113]
	v_mfma_f32_16x16x32_bf16 v[106:109], v[184:187], v[192:195], v[106:109]
	v_mfma_f32_16x16x32_bf16 v[102:105], v[176:179], v[200:203], v[102:105]
	v_mfma_f32_16x16x32_bf16 v[98:101], v[184:187], v[200:203], v[98:101]
	v_mfma_f32_16x16x32_bf16 v[78:81], v[176:179], v[208:211], v[78:81]
	v_mfma_f32_16x16x32_bf16 v[74:77], v[184:187], v[208:211], v[74:77]
	v_mfma_f32_16x16x32_bf16 v[70:73], v[176:179], v[216:219], v[70:73]
	v_mfma_f32_16x16x32_bf16 v[66:69], v[184:187], v[216:219], v[66:69]
	s_barrier
	s_setprio 0
	s_add_i32 s55, s44, s13
	v_lshl_add_u64 v[148:149], s[36:37], 0, v[134:135]
	s_mov_b32 m0, s55
	ds_read_b128 v[188:191], v155 offset:16384
	ds_read_b128 v[192:195], v155 offset:17408
	ds_read_b128 v[196:199], v155 offset:18432
	ds_read_b128 v[200:203], v155 offset:19456
	ds_read_b128 v[204:207], v155 offset:20480
	ds_read_b128 v[208:211], v155 offset:21504
	ds_read_b128 v[212:215], v155 offset:22528
	ds_read_b128 v[216:219], v155 offset:23552
	global_load_lds_dwordx4 v[148:149], off
	s_add_i32 m0, s55, 0x2000
	s_add_u32 s56, s36, 0x100000
	v_lshl_add_u64 v[220:221], s[36:37], 0, v[130:131]
	s_addc_u32 s57, s37, 0
	s_add_i32 s55, s45, s13
	global_load_lds_dwordx4 v[220:221], off
	v_lshl_add_u64 v[224:225], s[56:57], 0, v[134:135]
	s_mov_b32 m0, s55
	v_lshl_add_u64 v[226:227], s[38:39], 0, v[132:133]
	global_load_lds_dwordx4 v[224:225], off
	v_lshl_add_u64 v[224:225], s[56:57], 0, v[130:131]
	s_add_i32 m0, s55, 0x2000
	s_nop 0
	global_load_lds_dwordx4 v[224:225], off
	v_lshl_add_u64 v[224:225], s[38:39], 0, v[136:137]
	s_mov_b32 m0, s25
	s_nop 0
	global_load_lds_dwordx4 v[224:225], off
	s_mov_b32 m0, s31
	s_nop 0
	global_load_lds_dwordx4 v[226:227], off
	s_waitcnt vmcnt(8)
	s_waitcnt lgkmcnt(0)
	s_setprio 1
	s_barrier
	v_mfma_f32_16x16x32_bf16 v[62:65], v[156:159], v[188:191], 0
	v_mfma_f32_16x16x32_bf16 v[58:61], v[164:167], v[188:191], 0
	v_mfma_f32_16x16x32_bf16 v[54:57], v[156:159], v[196:199], 0
	v_mfma_f32_16x16x32_bf16 v[50:53], v[164:167], v[196:199], 0
	v_mfma_f32_16x16x32_bf16 v[30:33], v[156:159], v[204:207], 0
	v_mfma_f32_16x16x32_bf16 v[26:29], v[164:167], v[204:207], 0
	v_mfma_f32_16x16x32_bf16 v[22:25], v[156:159], v[212:215], 0
	v_mfma_f32_16x16x32_bf16 v[18:21], v[164:167], v[212:215], 0
	v_mfma_f32_16x16x32_bf16 v[62:65], v[160:163], v[192:195], v[62:65]
	v_mfma_f32_16x16x32_bf16 v[58:61], v[168:171], v[192:195], v[58:61]
	v_mfma_f32_16x16x32_bf16 v[54:57], v[160:163], v[200:203], v[54:57]
	v_mfma_f32_16x16x32_bf16 v[50:53], v[168:171], v[200:203], v[50:53]
	v_mfma_f32_16x16x32_bf16 v[30:33], v[160:163], v[208:211], v[30:33]
	v_mfma_f32_16x16x32_bf16 v[26:29], v[168:171], v[208:211], v[26:29]
	v_mfma_f32_16x16x32_bf16 v[22:25], v[160:163], v[216:219], v[22:25]
	v_mfma_f32_16x16x32_bf16 v[18:21], v[168:171], v[216:219], v[18:21]
	v_mfma_f32_16x16x32_bf16 v[46:49], v[172:175], v[188:191], 0
	v_mfma_f32_16x16x32_bf16 v[42:45], v[180:183], v[188:191], 0
	v_mfma_f32_16x16x32_bf16 v[38:41], v[172:175], v[196:199], 0
	v_mfma_f32_16x16x32_bf16 v[34:37], v[180:183], v[196:199], 0
	v_mfma_f32_16x16x32_bf16 v[14:17], v[172:175], v[204:207], 0
	v_mfma_f32_16x16x32_bf16 v[10:13], v[180:183], v[204:207], 0
	v_mfma_f32_16x16x32_bf16 v[6:9], v[172:175], v[212:215], 0
	v_mfma_f32_16x16x32_bf16 v[2:5], v[180:183], v[212:215], 0
	v_mfma_f32_16x16x32_bf16 v[46:49], v[176:179], v[192:195], v[46:49]
	v_mfma_f32_16x16x32_bf16 v[42:45], v[184:187], v[192:195], v[42:45]
	v_mfma_f32_16x16x32_bf16 v[38:41], v[176:179], v[200:203], v[38:41]
	v_mfma_f32_16x16x32_bf16 v[34:37], v[184:187], v[200:203], v[34:37]
	v_mfma_f32_16x16x32_bf16 v[14:17], v[176:179], v[208:211], v[14:17]
	v_mfma_f32_16x16x32_bf16 v[10:13], v[184:187], v[208:211], v[10:13]
	v_mfma_f32_16x16x32_bf16 v[6:9], v[176:179], v[216:219], v[6:9]
	v_mfma_f32_16x16x32_bf16 v[2:5], v[184:187], v[216:219], v[2:5]
	s_barrier
	s_setprio 0
	s_add_i32 s55, 0, 0x18000
	s_add_i32 s56, 0, 0x1c000
	v_add_u32_e32 v168, s55, v151
	v_add_u32_e32 v184, s56, v151
	ds_read_b128 v[156:159], v168
	ds_read_b128 v[160:163], v168 offset:1024
	ds_read_b128 v[164:167], v168 offset:2048
	ds_read_b128 v[168:171], v168 offset:3072
	ds_read_b128 v[172:175], v184
	ds_read_b128 v[176:179], v184 offset:1024
	ds_read_b128 v[180:183], v184 offset:2048
	ds_read_b128 v[184:187], v184 offset:3072
	s_add_u32 s38, s38, 0x100000
	s_addc_u32 s39, s39, 0
	s_mov_b32 m0, s34
	v_lshl_add_u64 v[228:229], s[38:39], 0, v[136:137]
	ds_read_b128 v[188:191], v155 offset:32768
	ds_read_b128 v[192:195], v155 offset:33792
	ds_read_b128 v[196:199], v155 offset:34816
	ds_read_b128 v[200:203], v155 offset:35840
	ds_read_b128 v[204:207], v155 offset:36864
	ds_read_b128 v[208:211], v155 offset:37888
	ds_read_b128 v[212:215], v155 offset:38912
	ds_read_b128 v[216:219], v155 offset:39936
	global_load_lds_dwordx4 v[228:229], off
	v_lshl_add_u64 v[228:229], s[38:39], 0, v[132:133]
	s_mov_b32 m0, s35
	s_nop 0
	global_load_lds_dwordx4 v[228:229], off
	s_waitcnt vmcnt(8)
	s_waitcnt lgkmcnt(0)
	s_setprio 1
	s_barrier
	v_mfma_f32_16x16x32_bf16 v[126:129], v[156:159], v[188:191], v[126:129]
	v_mfma_f32_16x16x32_bf16 v[122:125], v[164:167], v[188:191], v[122:125]
	v_mfma_f32_16x16x32_bf16 v[118:121], v[156:159], v[196:199], v[118:121]
	v_mfma_f32_16x16x32_bf16 v[114:117], v[164:167], v[196:199], v[114:117]
	v_mfma_f32_16x16x32_bf16 v[94:97], v[156:159], v[204:207], v[94:97]
	v_mfma_f32_16x16x32_bf16 v[90:93], v[164:167], v[204:207], v[90:93]
	v_mfma_f32_16x16x32_bf16 v[86:89], v[156:159], v[212:215], v[86:89]
	v_mfma_f32_16x16x32_bf16 v[82:85], v[164:167], v[212:215], v[82:85]
	v_mfma_f32_16x16x32_bf16 v[126:129], v[160:163], v[192:195], v[126:129]
	v_mfma_f32_16x16x32_bf16 v[122:125], v[168:171], v[192:195], v[122:125]
	v_mfma_f32_16x16x32_bf16 v[118:121], v[160:163], v[200:203], v[118:121]
	v_mfma_f32_16x16x32_bf16 v[114:117], v[168:171], v[200:203], v[114:117]
	v_mfma_f32_16x16x32_bf16 v[94:97], v[160:163], v[208:211], v[94:97]
	v_mfma_f32_16x16x32_bf16 v[90:93], v[168:171], v[208:211], v[90:93]
	v_mfma_f32_16x16x32_bf16 v[86:89], v[160:163], v[216:219], v[86:89]
	v_mfma_f32_16x16x32_bf16 v[82:85], v[168:171], v[216:219], v[82:85]
	v_mfma_f32_16x16x32_bf16 v[110:113], v[172:175], v[188:191], v[110:113]
	v_mfma_f32_16x16x32_bf16 v[106:109], v[180:183], v[188:191], v[106:109]
	v_mfma_f32_16x16x32_bf16 v[102:105], v[172:175], v[196:199], v[102:105]
	v_mfma_f32_16x16x32_bf16 v[98:101], v[180:183], v[196:199], v[98:101]
	v_mfma_f32_16x16x32_bf16 v[78:81], v[172:175], v[204:207], v[78:81]
	v_mfma_f32_16x16x32_bf16 v[74:77], v[180:183], v[204:207], v[74:77]
	v_mfma_f32_16x16x32_bf16 v[70:73], v[172:175], v[212:215], v[70:73]
	v_mfma_f32_16x16x32_bf16 v[66:69], v[180:183], v[212:215], v[66:69]
	v_mfma_f32_16x16x32_bf16 v[110:113], v[176:179], v[192:195], v[110:113]
	v_mfma_f32_16x16x32_bf16 v[106:109], v[184:187], v[192:195], v[106:109]
	v_mfma_f32_16x16x32_bf16 v[102:105], v[176:179], v[200:203], v[102:105]
	v_mfma_f32_16x16x32_bf16 v[98:101], v[184:187], v[200:203], v[98:101]
	v_mfma_f32_16x16x32_bf16 v[78:81], v[176:179], v[208:211], v[78:81]
	v_mfma_f32_16x16x32_bf16 v[74:77], v[184:187], v[208:211], v[74:77]
	v_mfma_f32_16x16x32_bf16 v[70:73], v[176:179], v[216:219], v[70:73]
	v_mfma_f32_16x16x32_bf16 v[66:69], v[184:187], v[216:219], v[66:69]
	s_barrier
	s_setprio 0
	s_add_i32 s38, s55, s13
	v_lshl_add_u64 v[148:149], v[148:149], 0, s[6:7]
	s_mov_b32 m0, s38
	ds_read_b128 v[188:191], v155 offset:49152
	ds_read_b128 v[192:195], v155 offset:50176
	ds_read_b128 v[196:199], v155 offset:51200
	ds_read_b128 v[200:203], v155 offset:52224
	ds_read_b128 v[204:207], v155 offset:53248
	ds_read_b128 v[208:211], v155 offset:54272
	ds_read_b128 v[212:215], v155 offset:55296
	ds_read_b128 v[216:219], v155 offset:56320
	global_load_lds_dwordx4 v[148:149], off
	s_add_i32 m0, s38, 0x2000
	s_add_u32 s36, s36, 0x100080
	v_lshl_add_u64 v[148:149], v[220:221], 0, s[6:7]
	s_addc_u32 s37, s37, 0
	s_add_i32 s38, s56, s13
	global_load_lds_dwordx4 v[148:149], off
	v_lshl_add_u64 v[148:149], s[36:37], 0, v[134:135]
	s_mov_b32 m0, s38
	s_nop 0
	global_load_lds_dwordx4 v[148:149], off
	v_lshl_add_u64 v[148:149], s[36:37], 0, v[130:131]
	s_add_i32 m0, s38, 0x2000
	s_nop 0
	global_load_lds_dwordx4 v[148:149], off
	v_lshl_add_u64 v[148:149], v[224:225], 0, s[6:7]
	s_mov_b32 m0, s41
	s_nop 0
	global_load_lds_dwordx4 v[148:149], off
	v_lshl_add_u64 v[148:149], v[226:227], 0, s[6:7]
	s_mov_b32 m0, s42
	s_nop 0
	global_load_lds_dwordx4 v[148:149], off
	s_waitcnt vmcnt(8)
	s_waitcnt lgkmcnt(0)
	s_nop 0
	s_setprio 1
	s_barrier
	v_mfma_f32_16x16x32_bf16 v[62:65], v[156:159], v[188:191], v[62:65]
	v_mfma_f32_16x16x32_bf16 v[58:61], v[164:167], v[188:191], v[58:61]
	v_mfma_f32_16x16x32_bf16 v[54:57], v[156:159], v[196:199], v[54:57]
	v_mfma_f32_16x16x32_bf16 v[50:53], v[164:167], v[196:199], v[50:53]
	v_mfma_f32_16x16x32_bf16 v[30:33], v[156:159], v[204:207], v[30:33]
	v_mfma_f32_16x16x32_bf16 v[26:29], v[164:167], v[204:207], v[26:29]
	v_mfma_f32_16x16x32_bf16 v[22:25], v[156:159], v[212:215], v[22:25]
	v_mfma_f32_16x16x32_bf16 v[18:21], v[164:167], v[212:215], v[18:21]
	v_mfma_f32_16x16x32_bf16 v[62:65], v[160:163], v[192:195], v[62:65]
	v_mfma_f32_16x16x32_bf16 v[58:61], v[168:171], v[192:195], v[58:61]
	v_mfma_f32_16x16x32_bf16 v[54:57], v[160:163], v[200:203], v[54:57]
	v_mfma_f32_16x16x32_bf16 v[50:53], v[168:171], v[200:203], v[50:53]
	v_mfma_f32_16x16x32_bf16 v[30:33], v[160:163], v[208:211], v[30:33]
	v_mfma_f32_16x16x32_bf16 v[26:29], v[168:171], v[208:211], v[26:29]
	v_mfma_f32_16x16x32_bf16 v[22:25], v[160:163], v[216:219], v[22:25]
	v_mfma_f32_16x16x32_bf16 v[18:21], v[168:171], v[216:219], v[18:21]
	v_mfma_f32_16x16x32_bf16 v[46:49], v[172:175], v[188:191], v[46:49]
	v_mfma_f32_16x16x32_bf16 v[42:45], v[180:183], v[188:191], v[42:45]
	v_mfma_f32_16x16x32_bf16 v[38:41], v[172:175], v[196:199], v[38:41]
	v_mfma_f32_16x16x32_bf16 v[34:37], v[180:183], v[196:199], v[34:37]
	v_mfma_f32_16x16x32_bf16 v[14:17], v[172:175], v[204:207], v[14:17]
	v_mfma_f32_16x16x32_bf16 v[10:13], v[180:183], v[204:207], v[10:13]
	v_mfma_f32_16x16x32_bf16 v[6:9], v[172:175], v[212:215], v[6:9]
	v_mfma_f32_16x16x32_bf16 v[2:5], v[180:183], v[212:215], v[2:5]
	v_mfma_f32_16x16x32_bf16 v[46:49], v[176:179], v[192:195], v[46:49]
	v_mfma_f32_16x16x32_bf16 v[42:45], v[184:187], v[192:195], v[42:45]
	v_mfma_f32_16x16x32_bf16 v[38:41], v[176:179], v[200:203], v[38:41]
	v_mfma_f32_16x16x32_bf16 v[34:37], v[184:187], v[200:203], v[34:37]
	v_mfma_f32_16x16x32_bf16 v[14:17], v[176:179], v[208:211], v[14:17]
	v_mfma_f32_16x16x32_bf16 v[10:13], v[184:187], v[208:211], v[10:13]
	v_mfma_f32_16x16x32_bf16 v[6:9], v[176:179], v[216:219], v[6:9]
	v_mfma_f32_16x16x32_bf16 v[2:5], v[184:187], v[216:219], v[2:5]
	s_barrier
	s_setprio 0
	s_add_i32 s54, s54, 2
	s_add_u32 s26, s26, 0x100
	s_addc_u32 s27, s27, 0
	s_add_u32 s52, s52, 0x100
	s_addc_u32 s53, s53, 0
.LBB0_788:
	ds_read_b128 v[156:159], v153
	ds_read_b128 v[160:163], v153 offset:1024
	ds_read_b128 v[164:167], v153 offset:2048
	ds_read_b128 v[168:171], v153 offset:3072
	ds_read_b128 v[172:175], v154
	ds_read_b128 v[176:179], v154 offset:1024
	ds_read_b128 v[180:183], v154 offset:2048
	ds_read_b128 v[184:187], v154 offset:3072
	s_add_u32 s36, s26, 0xfff00080
	s_addc_u32 s37, s27, -1
	s_cmp_eq_u32 s54, 60
	s_cselect_b32 s39, s19, s37
	s_cselect_b32 s38, s50, s36
	s_cselect_b32 s37, s17, s53
	s_cselect_b32 s36, s51, s52
	v_lshl_add_u64 v[148:149], s[26:27], 0, v[140:141]
	s_add_i32 m0, s25, 0xc000
	ds_read_b128 v[188:191], v155
	ds_read_b128 v[192:195], v155 offset:1024
	ds_read_b128 v[196:199], v155 offset:2048
	ds_read_b128 v[200:203], v155 offset:3072
	ds_read_b128 v[204:207], v155 offset:4096
	ds_read_b128 v[208:211], v155 offset:5120
	ds_read_b128 v[212:215], v155 offset:6144
	ds_read_b128 v[216:219], v155 offset:7168
	global_load_lds_dwordx4 v[148:149], off
	v_lshl_add_u64 v[148:149], s[26:27], 0, v[142:143]
	s_add_i32 m0, s25, 0xe000
	s_nop 0
	global_load_lds_dwordx4 v[148:149], off
	s_waitcnt vmcnt(8)
	s_waitcnt lgkmcnt(0)
	s_setprio 1
	s_barrier
	v_mfma_f32_16x16x32_bf16 v[126:129], v[156:159], v[188:191], v[126:129]
	v_mfma_f32_16x16x32_bf16 v[122:125], v[164:167], v[188:191], v[122:125]
	v_mfma_f32_16x16x32_bf16 v[118:121], v[156:159], v[196:199], v[118:121]
	v_mfma_f32_16x16x32_bf16 v[114:117], v[164:167], v[196:199], v[114:117]
	v_mfma_f32_16x16x32_bf16 v[94:97], v[156:159], v[204:207], v[94:97]
	v_mfma_f32_16x16x32_bf16 v[90:93], v[164:167], v[204:207], v[90:93]
	v_mfma_f32_16x16x32_bf16 v[86:89], v[156:159], v[212:215], v[86:89]
	v_mfma_f32_16x16x32_bf16 v[82:85], v[164:167], v[212:215], v[82:85]
	v_mfma_f32_16x16x32_bf16 v[126:129], v[160:163], v[192:195], v[126:129]
	v_mfma_f32_16x16x32_bf16 v[122:125], v[168:171], v[192:195], v[122:125]
	v_mfma_f32_16x16x32_bf16 v[118:121], v[160:163], v[200:203], v[118:121]
	v_mfma_f32_16x16x32_bf16 v[114:117], v[168:171], v[200:203], v[114:117]
	v_mfma_f32_16x16x32_bf16 v[94:97], v[160:163], v[208:211], v[94:97]
	v_mfma_f32_16x16x32_bf16 v[90:93], v[168:171], v[208:211], v[90:93]
	v_mfma_f32_16x16x32_bf16 v[86:89], v[160:163], v[216:219], v[86:89]
	v_mfma_f32_16x16x32_bf16 v[82:85], v[168:171], v[216:219], v[82:85]
	v_mfma_f32_16x16x32_bf16 v[110:113], v[172:175], v[188:191], v[110:113]
	v_mfma_f32_16x16x32_bf16 v[106:109], v[180:183], v[188:191], v[106:109]
	v_mfma_f32_16x16x32_bf16 v[102:105], v[172:175], v[196:199], v[102:105]
	v_mfma_f32_16x16x32_bf16 v[98:101], v[180:183], v[196:199], v[98:101]
	v_mfma_f32_16x16x32_bf16 v[78:81], v[172:175], v[204:207], v[78:81]
	v_mfma_f32_16x16x32_bf16 v[74:77], v[180:183], v[204:207], v[74:77]
	v_mfma_f32_16x16x32_bf16 v[70:73], v[172:175], v[212:215], v[70:73]
	v_mfma_f32_16x16x32_bf16 v[66:69], v[180:183], v[212:215], v[66:69]
	v_mfma_f32_16x16x32_bf16 v[110:113], v[176:179], v[192:195], v[110:113]
	v_mfma_f32_16x16x32_bf16 v[106:109], v[184:187], v[192:195], v[106:109]
	v_mfma_f32_16x16x32_bf16 v[102:105], v[176:179], v[200:203], v[102:105]
	v_mfma_f32_16x16x32_bf16 v[98:101], v[184:187], v[200:203], v[98:101]
	v_mfma_f32_16x16x32_bf16 v[78:81], v[176:179], v[208:211], v[78:81]
	v_mfma_f32_16x16x32_bf16 v[74:77], v[184:187], v[208:211], v[74:77]
	v_mfma_f32_16x16x32_bf16 v[70:73], v[176:179], v[216:219], v[70:73]
	v_mfma_f32_16x16x32_bf16 v[66:69], v[184:187], v[216:219], v[66:69]
	s_barrier
	s_setprio 0
	s_add_i32 s55, s44, s13
	v_lshl_add_u64 v[148:149], s[36:37], 0, v[134:135]
	s_mov_b32 m0, s55
	ds_read_b128 v[188:191], v155 offset:16384
	ds_read_b128 v[192:195], v155 offset:17408
	ds_read_b128 v[196:199], v155 offset:18432
	ds_read_b128 v[200:203], v155 offset:19456
	ds_read_b128 v[204:207], v155 offset:20480
	ds_read_b128 v[208:211], v155 offset:21504
	ds_read_b128 v[212:215], v155 offset:22528
	ds_read_b128 v[216:219], v155 offset:23552
	global_load_lds_dwordx4 v[148:149], off
	s_add_i32 m0, s55, 0x2000
	s_add_u32 s56, s36, 0x100000
	v_lshl_add_u64 v[220:221], s[36:37], 0, v[130:131]
	s_addc_u32 s57, s37, 0
	s_add_i32 s55, s45, s13
	global_load_lds_dwordx4 v[220:221], off
	v_lshl_add_u64 v[224:225], s[56:57], 0, v[134:135]
	s_mov_b32 m0, s55
	v_lshl_add_u64 v[226:227], s[38:39], 0, v[132:133]
	global_load_lds_dwordx4 v[224:225], off
	v_lshl_add_u64 v[224:225], s[56:57], 0, v[130:131]
	s_add_i32 m0, s55, 0x2000
	s_nop 0
	global_load_lds_dwordx4 v[224:225], off
	v_lshl_add_u64 v[224:225], s[38:39], 0, v[136:137]
	s_mov_b32 m0, s25
	s_nop 0
	global_load_lds_dwordx4 v[224:225], off
	s_mov_b32 m0, s31
	s_nop 0
	global_load_lds_dwordx4 v[226:227], off
	s_waitcnt vmcnt(8)
	s_waitcnt lgkmcnt(0)
	s_setprio 1
	s_barrier
	v_mfma_f32_16x16x32_bf16 v[62:65], v[156:159], v[188:191], v[62:65]
	v_mfma_f32_16x16x32_bf16 v[58:61], v[164:167], v[188:191], v[58:61]
	v_mfma_f32_16x16x32_bf16 v[54:57], v[156:159], v[196:199], v[54:57]
	v_mfma_f32_16x16x32_bf16 v[50:53], v[164:167], v[196:199], v[50:53]
	v_mfma_f32_16x16x32_bf16 v[30:33], v[156:159], v[204:207], v[30:33]
	v_mfma_f32_16x16x32_bf16 v[26:29], v[164:167], v[204:207], v[26:29]
	v_mfma_f32_16x16x32_bf16 v[22:25], v[156:159], v[212:215], v[22:25]
	v_mfma_f32_16x16x32_bf16 v[18:21], v[164:167], v[212:215], v[18:21]
	v_mfma_f32_16x16x32_bf16 v[62:65], v[160:163], v[192:195], v[62:65]
	v_mfma_f32_16x16x32_bf16 v[58:61], v[168:171], v[192:195], v[58:61]
	v_mfma_f32_16x16x32_bf16 v[54:57], v[160:163], v[200:203], v[54:57]
	v_mfma_f32_16x16x32_bf16 v[50:53], v[168:171], v[200:203], v[50:53]
	v_mfma_f32_16x16x32_bf16 v[30:33], v[160:163], v[208:211], v[30:33]
	v_mfma_f32_16x16x32_bf16 v[26:29], v[168:171], v[208:211], v[26:29]
	v_mfma_f32_16x16x32_bf16 v[22:25], v[160:163], v[216:219], v[22:25]
	v_mfma_f32_16x16x32_bf16 v[18:21], v[168:171], v[216:219], v[18:21]
	v_mfma_f32_16x16x32_bf16 v[46:49], v[172:175], v[188:191], v[46:49]
	v_mfma_f32_16x16x32_bf16 v[42:45], v[180:183], v[188:191], v[42:45]
	v_mfma_f32_16x16x32_bf16 v[38:41], v[172:175], v[196:199], v[38:41]
	v_mfma_f32_16x16x32_bf16 v[34:37], v[180:183], v[196:199], v[34:37]
	v_mfma_f32_16x16x32_bf16 v[14:17], v[172:175], v[204:207], v[14:17]
	v_mfma_f32_16x16x32_bf16 v[10:13], v[180:183], v[204:207], v[10:13]
	v_mfma_f32_16x16x32_bf16 v[6:9], v[172:175], v[212:215], v[6:9]
	v_mfma_f32_16x16x32_bf16 v[2:5], v[180:183], v[212:215], v[2:5]
	v_mfma_f32_16x16x32_bf16 v[46:49], v[176:179], v[192:195], v[46:49]
	v_mfma_f32_16x16x32_bf16 v[42:45], v[184:187], v[192:195], v[42:45]
	v_mfma_f32_16x16x32_bf16 v[38:41], v[176:179], v[200:203], v[38:41]
	v_mfma_f32_16x16x32_bf16 v[34:37], v[184:187], v[200:203], v[34:37]
	v_mfma_f32_16x16x32_bf16 v[14:17], v[176:179], v[208:211], v[14:17]
	v_mfma_f32_16x16x32_bf16 v[10:13], v[184:187], v[208:211], v[10:13]
	v_mfma_f32_16x16x32_bf16 v[6:9], v[176:179], v[216:219], v[6:9]
	v_mfma_f32_16x16x32_bf16 v[2:5], v[184:187], v[216:219], v[2:5]
	s_barrier
	s_setprio 0
	s_add_i32 s55, 0, 0x18000
	s_add_i32 s56, 0, 0x1c000
	v_add_u32_e32 v168, s55, v151
	v_add_u32_e32 v184, s56, v151
	ds_read_b128 v[156:159], v168
	ds_read_b128 v[160:163], v168 offset:1024
	ds_read_b128 v[164:167], v168 offset:2048
	ds_read_b128 v[168:171], v168 offset:3072
	ds_read_b128 v[172:175], v184
	ds_read_b128 v[176:179], v184 offset:1024
	ds_read_b128 v[180:183], v184 offset:2048
	ds_read_b128 v[184:187], v184 offset:3072
	s_add_u32 s38, s38, 0x100000
	s_addc_u32 s39, s39, 0
	s_mov_b32 m0, s34
	v_lshl_add_u64 v[228:229], s[38:39], 0, v[136:137]
	ds_read_b128 v[188:191], v155 offset:32768
	ds_read_b128 v[192:195], v155 offset:33792
	ds_read_b128 v[196:199], v155 offset:34816
	ds_read_b128 v[200:203], v155 offset:35840
	ds_read_b128 v[204:207], v155 offset:36864
	ds_read_b128 v[208:211], v155 offset:37888
	ds_read_b128 v[212:215], v155 offset:38912
	ds_read_b128 v[216:219], v155 offset:39936
	global_load_lds_dwordx4 v[228:229], off
	v_lshl_add_u64 v[228:229], s[38:39], 0, v[132:133]
	s_mov_b32 m0, s35
	s_nop 0
	global_load_lds_dwordx4 v[228:229], off
	s_waitcnt vmcnt(8)
	s_waitcnt lgkmcnt(0)
	s_setprio 1
	s_barrier
	v_mfma_f32_16x16x32_bf16 v[126:129], v[156:159], v[188:191], v[126:129]
	v_mfma_f32_16x16x32_bf16 v[122:125], v[164:167], v[188:191], v[122:125]
	v_mfma_f32_16x16x32_bf16 v[118:121], v[156:159], v[196:199], v[118:121]
	v_mfma_f32_16x16x32_bf16 v[114:117], v[164:167], v[196:199], v[114:117]
	v_mfma_f32_16x16x32_bf16 v[94:97], v[156:159], v[204:207], v[94:97]
	v_mfma_f32_16x16x32_bf16 v[90:93], v[164:167], v[204:207], v[90:93]
	v_mfma_f32_16x16x32_bf16 v[86:89], v[156:159], v[212:215], v[86:89]
	v_mfma_f32_16x16x32_bf16 v[82:85], v[164:167], v[212:215], v[82:85]
	v_mfma_f32_16x16x32_bf16 v[126:129], v[160:163], v[192:195], v[126:129]
	v_mfma_f32_16x16x32_bf16 v[122:125], v[168:171], v[192:195], v[122:125]
	v_mfma_f32_16x16x32_bf16 v[118:121], v[160:163], v[200:203], v[118:121]
	v_mfma_f32_16x16x32_bf16 v[114:117], v[168:171], v[200:203], v[114:117]
	v_mfma_f32_16x16x32_bf16 v[94:97], v[160:163], v[208:211], v[94:97]
	v_mfma_f32_16x16x32_bf16 v[90:93], v[168:171], v[208:211], v[90:93]
	v_mfma_f32_16x16x32_bf16 v[86:89], v[160:163], v[216:219], v[86:89]
	v_mfma_f32_16x16x32_bf16 v[82:85], v[168:171], v[216:219], v[82:85]
	v_mfma_f32_16x16x32_bf16 v[110:113], v[172:175], v[188:191], v[110:113]
	v_mfma_f32_16x16x32_bf16 v[106:109], v[180:183], v[188:191], v[106:109]
	v_mfma_f32_16x16x32_bf16 v[102:105], v[172:175], v[196:199], v[102:105]
	v_mfma_f32_16x16x32_bf16 v[98:101], v[180:183], v[196:199], v[98:101]
	v_mfma_f32_16x16x32_bf16 v[78:81], v[172:175], v[204:207], v[78:81]
	v_mfma_f32_16x16x32_bf16 v[74:77], v[180:183], v[204:207], v[74:77]
	v_mfma_f32_16x16x32_bf16 v[70:73], v[172:175], v[212:215], v[70:73]
	v_mfma_f32_16x16x32_bf16 v[66:69], v[180:183], v[212:215], v[66:69]
	v_mfma_f32_16x16x32_bf16 v[110:113], v[176:179], v[192:195], v[110:113]
	v_mfma_f32_16x16x32_bf16 v[106:109], v[184:187], v[192:195], v[106:109]
	v_mfma_f32_16x16x32_bf16 v[102:105], v[176:179], v[200:203], v[102:105]
	v_mfma_f32_16x16x32_bf16 v[98:101], v[184:187], v[200:203], v[98:101]
	v_mfma_f32_16x16x32_bf16 v[78:81], v[176:179], v[208:211], v[78:81]
	v_mfma_f32_16x16x32_bf16 v[74:77], v[184:187], v[208:211], v[74:77]
	v_mfma_f32_16x16x32_bf16 v[70:73], v[176:179], v[216:219], v[70:73]
	v_mfma_f32_16x16x32_bf16 v[66:69], v[184:187], v[216:219], v[66:69]
	s_barrier
	s_setprio 0
	s_add_i32 s38, s55, s13
	v_lshl_add_u64 v[148:149], v[148:149], 0, s[6:7]
	s_mov_b32 m0, s38
	ds_read_b128 v[188:191], v155 offset:49152
	ds_read_b128 v[192:195], v155 offset:50176
	ds_read_b128 v[196:199], v155 offset:51200
	ds_read_b128 v[200:203], v155 offset:52224
	ds_read_b128 v[204:207], v155 offset:53248
	ds_read_b128 v[208:211], v155 offset:54272
	ds_read_b128 v[212:215], v155 offset:55296
	ds_read_b128 v[216:219], v155 offset:56320
	global_load_lds_dwordx4 v[148:149], off
	s_add_i32 m0, s38, 0x2000
	s_add_u32 s36, s36, 0x100080
	v_lshl_add_u64 v[148:149], v[220:221], 0, s[6:7]
	s_addc_u32 s37, s37, 0
	s_add_i32 s38, s56, s13
	global_load_lds_dwordx4 v[148:149], off
	v_lshl_add_u64 v[148:149], s[36:37], 0, v[134:135]
	s_mov_b32 m0, s38
	s_nop 0
	global_load_lds_dwordx4 v[148:149], off
	v_lshl_add_u64 v[148:149], s[36:37], 0, v[130:131]
	s_add_i32 m0, s38, 0x2000
	s_nop 0
	global_load_lds_dwordx4 v[148:149], off
	v_lshl_add_u64 v[148:149], v[224:225], 0, s[6:7]
	s_mov_b32 m0, s41
	s_nop 0
	global_load_lds_dwordx4 v[148:149], off
	v_lshl_add_u64 v[148:149], v[226:227], 0, s[6:7]
	s_mov_b32 m0, s42
	s_nop 0
	global_load_lds_dwordx4 v[148:149], off
	s_waitcnt vmcnt(8)
	s_waitcnt lgkmcnt(0)
	s_nop 0
	s_setprio 1
	s_barrier
	v_mfma_f32_16x16x32_bf16 v[62:65], v[156:159], v[188:191], v[62:65]
	v_mfma_f32_16x16x32_bf16 v[58:61], v[164:167], v[188:191], v[58:61]
	v_mfma_f32_16x16x32_bf16 v[54:57], v[156:159], v[196:199], v[54:57]
	v_mfma_f32_16x16x32_bf16 v[50:53], v[164:167], v[196:199], v[50:53]
	v_mfma_f32_16x16x32_bf16 v[30:33], v[156:159], v[204:207], v[30:33]
	v_mfma_f32_16x16x32_bf16 v[26:29], v[164:167], v[204:207], v[26:29]
	v_mfma_f32_16x16x32_bf16 v[22:25], v[156:159], v[212:215], v[22:25]
	v_mfma_f32_16x16x32_bf16 v[18:21], v[164:167], v[212:215], v[18:21]
	v_mfma_f32_16x16x32_bf16 v[62:65], v[160:163], v[192:195], v[62:65]
	v_mfma_f32_16x16x32_bf16 v[58:61], v[168:171], v[192:195], v[58:61]
	v_mfma_f32_16x16x32_bf16 v[54:57], v[160:163], v[200:203], v[54:57]
	v_mfma_f32_16x16x32_bf16 v[50:53], v[168:171], v[200:203], v[50:53]
	v_mfma_f32_16x16x32_bf16 v[30:33], v[160:163], v[208:211], v[30:33]
	v_mfma_f32_16x16x32_bf16 v[26:29], v[168:171], v[208:211], v[26:29]
	v_mfma_f32_16x16x32_bf16 v[22:25], v[160:163], v[216:219], v[22:25]
	v_mfma_f32_16x16x32_bf16 v[18:21], v[168:171], v[216:219], v[18:21]
	v_mfma_f32_16x16x32_bf16 v[46:49], v[172:175], v[188:191], v[46:49]
	v_mfma_f32_16x16x32_bf16 v[42:45], v[180:183], v[188:191], v[42:45]
	v_mfma_f32_16x16x32_bf16 v[38:41], v[172:175], v[196:199], v[38:41]
	v_mfma_f32_16x16x32_bf16 v[34:37], v[180:183], v[196:199], v[34:37]
	v_mfma_f32_16x16x32_bf16 v[14:17], v[172:175], v[204:207], v[14:17]
	v_mfma_f32_16x16x32_bf16 v[10:13], v[180:183], v[204:207], v[10:13]
	v_mfma_f32_16x16x32_bf16 v[6:9], v[172:175], v[212:215], v[6:9]
	v_mfma_f32_16x16x32_bf16 v[2:5], v[180:183], v[212:215], v[2:5]
	v_mfma_f32_16x16x32_bf16 v[46:49], v[176:179], v[192:195], v[46:49]
	v_mfma_f32_16x16x32_bf16 v[42:45], v[184:187], v[192:195], v[42:45]
	v_mfma_f32_16x16x32_bf16 v[38:41], v[176:179], v[200:203], v[38:41]
	v_mfma_f32_16x16x32_bf16 v[34:37], v[184:187], v[200:203], v[34:37]
	v_mfma_f32_16x16x32_bf16 v[14:17], v[176:179], v[208:211], v[14:17]
	v_mfma_f32_16x16x32_bf16 v[10:13], v[184:187], v[208:211], v[10:13]
	v_mfma_f32_16x16x32_bf16 v[6:9], v[176:179], v[216:219], v[6:9]
	v_mfma_f32_16x16x32_bf16 v[2:5], v[184:187], v[216:219], v[2:5]
	s_barrier
	s_setprio 0
	s_add_i32 s54, s54, 2
	s_add_u32 s26, s26, 0x100
	s_addc_u32 s27, s27, 0
	s_add_u32 s52, s52, 0x100
	s_addc_u32 s53, s53, 0
	s_cmp_gt_u32 s54, 61
	s_cbranch_scc0 .LBB0_788
	s_and_b64 vcc, exec, s[8:9]
	s_cbranch_vccz .LBB0_791
	s_barrier

.Lpeeld:
	ds_read_b128 v[130:133], v207
	ds_read_b128 v[134:137], v207 offset:1024
	ds_read_b128 v[138:141], v207 offset:2048
	ds_read_b128 v[142:145], v207 offset:3072
	ds_read_b128 v[146:149], v208
	ds_read_b128 v[172:175], v208 offset:1024
	ds_read_b128 v[176:179], v208 offset:2048
	ds_read_b128 v[210:213], v208 offset:3072
	s_add_u32 s10, s8, 0xffd50080
	s_addc_u32 s11, s9, -1
	s_cmpk_eq_i32 s16, 0xa8
	s_cselect_b32 s13, s25, s11
	s_cselect_b32 s12, s24, s10
	s_cselect_b32 s11, s41, s15
	s_cselect_b32 s10, s40, s14
	v_lshl_add_u64 v[180:181], s[8:9], 0, v[166:167]
	s_add_i32 m0, s48, 0xc000
	ds_read_b128 v[214:217], v202
	ds_read_b128 v[218:221], v202 offset:1024
	ds_read_b128 v[224:227], v202 offset:2048
	ds_read_b128 v[228:231], v202 offset:3072
	ds_read_b128 v[232:235], v202 offset:4096
	ds_read_b128 v[236:239], v202 offset:5120
	ds_read_b128 v[240:243], v202 offset:6144
	ds_read_b128 v[244:247], v202 offset:7168
	global_load_lds_dwordx4 v[180:181], off
	v_lshl_add_u64 v[180:181], s[8:9], 0, v[168:169]
	s_add_i32 m0, s48, 0xe000
	s_nop 0
	global_load_lds_dwordx4 v[180:181], off
	s_waitcnt vmcnt(8)
	s_waitcnt lgkmcnt(0)
	s_setprio 1
	s_barrier
	v_mfma_f32_16x16x32_bf16 v[90:93], v[130:133], v[214:217], 0
	v_mfma_f32_16x16x32_bf16 v[74:77], v[138:141], v[214:217], 0
	v_mfma_f32_16x16x32_bf16 v[46:49], v[130:133], v[224:227], 0
	v_mfma_f32_16x16x32_bf16 v[42:45], v[138:141], v[224:227], 0
	v_mfma_f32_16x16x32_bf16 v[126:129], v[130:133], v[232:235], 0
	v_mfma_f32_16x16x32_bf16 v[122:125], v[138:141], v[232:235], 0
	v_mfma_f32_16x16x32_bf16 v[110:113], v[130:133], v[240:243], 0
	v_mfma_f32_16x16x32_bf16 v[106:109], v[138:141], v[240:243], 0
	v_mfma_f32_16x16x32_bf16 v[90:93], v[134:137], v[218:221], v[90:93]
	v_mfma_f32_16x16x32_bf16 v[74:77], v[142:145], v[218:221], v[74:77]
	v_mfma_f32_16x16x32_bf16 v[46:49], v[134:137], v[228:231], v[46:49]
	v_mfma_f32_16x16x32_bf16 v[42:45], v[142:145], v[228:231], v[42:45]
	v_mfma_f32_16x16x32_bf16 v[126:129], v[134:137], v[236:239], v[126:129]
	v_mfma_f32_16x16x32_bf16 v[122:125], v[142:145], v[236:239], v[122:125]
	v_mfma_f32_16x16x32_bf16 v[110:113], v[134:137], v[244:247], v[110:113]
	v_mfma_f32_16x16x32_bf16 v[106:109], v[142:145], v[244:247], v[106:109]
	v_mfma_f32_16x16x32_bf16 v[70:73], v[146:149], v[214:217], 0
	v_mfma_f32_16x16x32_bf16 v[66:69], v[176:179], v[214:217], 0
	v_mfma_f32_16x16x32_bf16 v[34:37], v[146:149], v[224:227], 0
	v_mfma_f32_16x16x32_bf16 v[38:41], v[176:179], v[224:227], 0
	v_mfma_f32_16x16x32_bf16 v[118:121], v[146:149], v[232:235], 0
	v_mfma_f32_16x16x32_bf16 v[114:117], v[176:179], v[232:235], 0
	v_mfma_f32_16x16x32_bf16 v[102:105], v[146:149], v[240:243], 0
	v_mfma_f32_16x16x32_bf16 v[98:101], v[176:179], v[240:243], 0
	v_mfma_f32_16x16x32_bf16 v[70:73], v[172:175], v[218:221], v[70:73]
	v_mfma_f32_16x16x32_bf16 v[66:69], v[210:213], v[218:221], v[66:69]
	v_mfma_f32_16x16x32_bf16 v[34:37], v[172:175], v[228:231], v[34:37]
	v_mfma_f32_16x16x32_bf16 v[38:41], v[210:213], v[228:231], v[38:41]
	v_mfma_f32_16x16x32_bf16 v[118:121], v[172:175], v[236:239], v[118:121]
	v_mfma_f32_16x16x32_bf16 v[114:117], v[210:213], v[236:239], v[114:117]
	v_mfma_f32_16x16x32_bf16 v[102:105], v[172:175], v[244:247], v[102:105]
	v_mfma_f32_16x16x32_bf16 v[98:101], v[210:213], v[244:247], v[98:101]
	s_barrier
	s_setprio 0
	s_add_i32 s17, s57, s46
	v_lshl_add_u64 v[180:181], s[10:11], 0, v[150:151]
	s_mov_b32 m0, s17
	ds_read_b128 v[214:217], v202 offset:16384
	ds_read_b128 v[218:221], v202 offset:17408
	ds_read_b128 v[224:227], v202 offset:18432
	ds_read_b128 v[228:231], v202 offset:19456
	ds_read_b128 v[232:235], v202 offset:20480
	ds_read_b128 v[236:239], v202 offset:21504
	ds_read_b128 v[240:243], v202 offset:22528
	ds_read_b128 v[244:247], v202 offset:23552
	global_load_lds_dwordx4 v[180:181], off
	s_add_i32 m0, s17, 0x2000
	s_add_u32 s18, s10, 0x2b0000
	v_lshl_add_u64 v[248:249], s[10:11], 0, v[152:153]
	s_addc_u32 s19, s11, 0
	s_add_i32 s17, s58, s46
	global_load_lds_dwordx4 v[248:249], off
	v_lshl_add_u64 v[250:251], s[18:19], 0, v[150:151]
	s_mov_b32 m0, s17
	v_lshl_add_u64 v[252:253], s[12:13], 0, v[152:153]
	global_load_lds_dwordx4 v[250:251], off
	v_lshl_add_u64 v[250:251], s[18:19], 0, v[152:153]
	s_add_i32 m0, s17, 0x2000
	s_nop 0
	global_load_lds_dwordx4 v[250:251], off
	v_lshl_add_u64 v[250:251], s[12:13], 0, v[150:151]
	s_mov_b32 m0, s48
	s_nop 0
	global_load_lds_dwordx4 v[250:251], off
	s_mov_b32 m0, s49
	s_nop 0
	global_load_lds_dwordx4 v[252:253], off
	s_waitcnt vmcnt(8)
	s_waitcnt lgkmcnt(0)
	s_setprio 1
	s_barrier
	v_mfma_f32_16x16x32_bf16 v[94:97], v[130:133], v[214:217], 0
	v_mfma_f32_16x16x32_bf16 v[86:89], v[138:141], v[214:217], 0
	v_mfma_f32_16x16x32_bf16 v[82:85], v[130:133], v[224:227], 0
	v_mfma_f32_16x16x32_bf16 v[78:81], v[138:141], v[224:227], 0
	v_mfma_f32_16x16x32_bf16 v[30:33], v[130:133], v[232:235], 0
	v_mfma_f32_16x16x32_bf16 v[26:29], v[138:141], v[232:235], 0
	v_mfma_f32_16x16x32_bf16 v[22:25], v[130:133], v[240:243], 0
	v_mfma_f32_16x16x32_bf16 v[18:21], v[138:141], v[240:243], 0
	v_mfma_f32_16x16x32_bf16 v[94:97], v[134:137], v[218:221], v[94:97]
	v_mfma_f32_16x16x32_bf16 v[86:89], v[142:145], v[218:221], v[86:89]
	v_mfma_f32_16x16x32_bf16 v[82:85], v[134:137], v[228:231], v[82:85]
	v_mfma_f32_16x16x32_bf16 v[78:81], v[142:145], v[228:231], v[78:81]
	v_mfma_f32_16x16x32_bf16 v[30:33], v[134:137], v[236:239], v[30:33]
	v_mfma_f32_16x16x32_bf16 v[26:29], v[142:145], v[236:239], v[26:29]
	v_mfma_f32_16x16x32_bf16 v[22:25], v[134:137], v[244:247], v[22:25]
	v_mfma_f32_16x16x32_bf16 v[18:21], v[142:145], v[244:247], v[18:21]
	v_mfma_f32_16x16x32_bf16 v[62:65], v[146:149], v[214:217], 0
	v_mfma_f32_16x16x32_bf16 v[58:61], v[176:179], v[214:217], 0
	v_mfma_f32_16x16x32_bf16 v[54:57], v[146:149], v[224:227], 0
	v_mfma_f32_16x16x32_bf16 v[50:53], v[176:179], v[224:227], 0
	v_mfma_f32_16x16x32_bf16 v[14:17], v[146:149], v[232:235], 0
	v_mfma_f32_16x16x32_bf16 v[6:9], v[176:179], v[232:235], 0
	v_mfma_f32_16x16x32_bf16 v[10:13], v[146:149], v[240:243], 0
	v_mfma_f32_16x16x32_bf16 v[2:5], v[176:179], v[240:243], 0
	v_mfma_f32_16x16x32_bf16 v[62:65], v[172:175], v[218:221], v[62:65]
	v_mfma_f32_16x16x32_bf16 v[58:61], v[210:213], v[218:221], v[58:61]
	v_mfma_f32_16x16x32_bf16 v[54:57], v[172:175], v[228:231], v[54:57]
	v_mfma_f32_16x16x32_bf16 v[50:53], v[210:213], v[228:231], v[50:53]
	v_mfma_f32_16x16x32_bf16 v[14:17], v[172:175], v[236:239], v[14:17]
	v_mfma_f32_16x16x32_bf16 v[6:9], v[210:213], v[236:239], v[6:9]
	v_mfma_f32_16x16x32_bf16 v[10:13], v[172:175], v[244:247], v[10:13]
	v_mfma_f32_16x16x32_bf16 v[2:5], v[210:213], v[244:247], v[2:5]
	s_barrier
	s_setprio 0
	s_add_i32 s17, 0, 0x18000
	s_add_i32 s18, 0, 0x1c000
	v_add_u32_e32 v142, s17, v182
	v_add_u32_e32 v154, s18, v182
	ds_read_b128 v[130:133], v142
	ds_read_b128 v[134:137], v142 offset:1024
	ds_read_b128 v[138:141], v142 offset:2048
	ds_read_b128 v[142:145], v142 offset:3072
	ds_read_b128 v[146:149], v154
	ds_read_b128 v[172:175], v154 offset:1024
	ds_read_b128 v[176:179], v154 offset:2048
	ds_read_b128 v[210:213], v154 offset:3072
	s_add_u32 s12, s12, 0x2b0000
	s_addc_u32 s13, s13, 0
	s_mov_b32 m0, s50
	v_lshl_add_u64 v[188:189], s[12:13], 0, v[150:151]
	ds_read_b128 v[214:217], v202 offset:32768
	ds_read_b128 v[218:221], v202 offset:33792
	ds_read_b128 v[224:227], v202 offset:34816
	ds_read_b128 v[228:231], v202 offset:35840
	ds_read_b128 v[232:235], v202 offset:36864
	ds_read_b128 v[236:239], v202 offset:37888
	ds_read_b128 v[240:243], v202 offset:38912
	ds_read_b128 v[244:247], v202 offset:39936
	global_load_lds_dwordx4 v[188:189], off
	v_lshl_add_u64 v[188:189], s[12:13], 0, v[152:153]
	s_mov_b32 m0, s51
	s_nop 0
	global_load_lds_dwordx4 v[188:189], off
	s_waitcnt vmcnt(8)
	s_waitcnt lgkmcnt(0)
	s_setprio 1
	s_barrier
	v_mfma_f32_16x16x32_bf16 v[90:93], v[130:133], v[214:217], v[90:93]
	v_mfma_f32_16x16x32_bf16 v[74:77], v[138:141], v[214:217], v[74:77]
	v_mfma_f32_16x16x32_bf16 v[46:49], v[130:133], v[224:227], v[46:49]
	v_mfma_f32_16x16x32_bf16 v[42:45], v[138:141], v[224:227], v[42:45]
	v_mfma_f32_16x16x32_bf16 v[126:129], v[130:133], v[232:235], v[126:129]
	v_mfma_f32_16x16x32_bf16 v[122:125], v[138:141], v[232:235], v[122:125]
	v_mfma_f32_16x16x32_bf16 v[110:113], v[130:133], v[240:243], v[110:113]
	v_mfma_f32_16x16x32_bf16 v[106:109], v[138:141], v[240:243], v[106:109]
	v_mfma_f32_16x16x32_bf16 v[90:93], v[134:137], v[218:221], v[90:93]
	v_mfma_f32_16x16x32_bf16 v[74:77], v[142:145], v[218:221], v[74:77]
	v_mfma_f32_16x16x32_bf16 v[46:49], v[134:137], v[228:231], v[46:49]
	v_mfma_f32_16x16x32_bf16 v[42:45], v[142:145], v[228:231], v[42:45]
	v_mfma_f32_16x16x32_bf16 v[126:129], v[134:137], v[236:239], v[126:129]
	v_mfma_f32_16x16x32_bf16 v[122:125], v[142:145], v[236:239], v[122:125]
	v_mfma_f32_16x16x32_bf16 v[110:113], v[134:137], v[244:247], v[110:113]
	v_mfma_f32_16x16x32_bf16 v[106:109], v[142:145], v[244:247], v[106:109]
	v_mfma_f32_16x16x32_bf16 v[70:73], v[146:149], v[214:217], v[70:73]
	v_mfma_f32_16x16x32_bf16 v[66:69], v[176:179], v[214:217], v[66:69]
	v_mfma_f32_16x16x32_bf16 v[34:37], v[146:149], v[224:227], v[34:37]
	v_mfma_f32_16x16x32_bf16 v[38:41], v[176:179], v[224:227], v[38:41]
	v_mfma_f32_16x16x32_bf16 v[118:121], v[146:149], v[232:235], v[118:121]
	v_mfma_f32_16x16x32_bf16 v[114:117], v[176:179], v[232:235], v[114:117]
	v_mfma_f32_16x16x32_bf16 v[102:105], v[146:149], v[240:243], v[102:105]
	v_mfma_f32_16x16x32_bf16 v[98:101], v[176:179], v[240:243], v[98:101]
	v_mfma_f32_16x16x32_bf16 v[70:73], v[172:175], v[218:221], v[70:73]
	v_mfma_f32_16x16x32_bf16 v[66:69], v[210:213], v[218:221], v[66:69]
	v_mfma_f32_16x16x32_bf16 v[34:37], v[172:175], v[228:231], v[34:37]
	v_mfma_f32_16x16x32_bf16 v[38:41], v[210:213], v[228:231], v[38:41]
	v_mfma_f32_16x16x32_bf16 v[118:121], v[172:175], v[236:239], v[118:121]
	v_mfma_f32_16x16x32_bf16 v[114:117], v[210:213], v[236:239], v[114:117]
	v_mfma_f32_16x16x32_bf16 v[102:105], v[172:175], v[244:247], v[102:105]
	v_mfma_f32_16x16x32_bf16 v[98:101], v[210:213], v[244:247], v[98:101]
	s_barrier
	s_setprio 0
	s_add_i32 s12, s17, s46
	v_lshl_add_u64 v[180:181], v[180:181], 0, s[30:31]
	s_mov_b32 m0, s12
	ds_read_b128 v[214:217], v202 offset:49152
	ds_read_b128 v[218:221], v202 offset:50176
	ds_read_b128 v[224:227], v202 offset:51200
	ds_read_b128 v[228:231], v202 offset:52224
	ds_read_b128 v[232:235], v202 offset:53248
	ds_read_b128 v[236:239], v202 offset:54272
	ds_read_b128 v[240:243], v202 offset:55296
	ds_read_b128 v[244:247], v202 offset:56320
	global_load_lds_dwordx4 v[180:181], off
	s_add_i32 m0, s12, 0x2000
	s_add_u32 s10, s10, 0x2b0080
	v_lshl_add_u64 v[180:181], v[248:249], 0, s[30:31]
	s_addc_u32 s11, s11, 0
	s_add_i32 s12, s18, s46
	global_load_lds_dwordx4 v[180:181], off
	v_lshl_add_u64 v[180:181], s[10:11], 0, v[150:151]
	s_mov_b32 m0, s12
	s_nop 0
	global_load_lds_dwordx4 v[180:181], off
	v_lshl_add_u64 v[180:181], s[10:11], 0, v[152:153]
	s_add_i32 m0, s12, 0x2000
	s_nop 0
	global_load_lds_dwordx4 v[180:181], off
	v_lshl_add_u64 v[180:181], v[250:251], 0, s[30:31]
	s_mov_b32 m0, s52
	s_nop 0
	global_load_lds_dwordx4 v[180:181], off
	v_lshl_add_u64 v[180:181], v[252:253], 0, s[30:31]
	s_mov_b32 m0, s53
	s_nop 0
	global_load_lds_dwordx4 v[180:181], off
	s_waitcnt vmcnt(8)
	s_waitcnt lgkmcnt(0)
	s_nop 0
	s_setprio 1
	s_barrier
	v_mfma_f32_16x16x32_bf16 v[94:97], v[130:133], v[214:217], v[94:97]
	v_mfma_f32_16x16x32_bf16 v[86:89], v[138:141], v[214:217], v[86:89]
	v_mfma_f32_16x16x32_bf16 v[82:85], v[130:133], v[224:227], v[82:85]
	v_mfma_f32_16x16x32_bf16 v[78:81], v[138:141], v[224:227], v[78:81]
	v_mfma_f32_16x16x32_bf16 v[30:33], v[130:133], v[232:235], v[30:33]
	v_mfma_f32_16x16x32_bf16 v[26:29], v[138:141], v[232:235], v[26:29]
	v_mfma_f32_16x16x32_bf16 v[22:25], v[130:133], v[240:243], v[22:25]
	v_mfma_f32_16x16x32_bf16 v[18:21], v[138:141], v[240:243], v[18:21]
	v_mfma_f32_16x16x32_bf16 v[94:97], v[134:137], v[218:221], v[94:97]
	v_mfma_f32_16x16x32_bf16 v[86:89], v[142:145], v[218:221], v[86:89]
	v_mfma_f32_16x16x32_bf16 v[82:85], v[134:137], v[228:231], v[82:85]
	v_mfma_f32_16x16x32_bf16 v[78:81], v[142:145], v[228:231], v[78:81]
	v_mfma_f32_16x16x32_bf16 v[30:33], v[134:137], v[236:239], v[30:33]
	v_mfma_f32_16x16x32_bf16 v[26:29], v[142:145], v[236:239], v[26:29]
	v_mfma_f32_16x16x32_bf16 v[22:25], v[134:137], v[244:247], v[22:25]
	v_mfma_f32_16x16x32_bf16 v[18:21], v[142:145], v[244:247], v[18:21]
	v_mfma_f32_16x16x32_bf16 v[62:65], v[146:149], v[214:217], v[62:65]
	v_mfma_f32_16x16x32_bf16 v[58:61], v[176:179], v[214:217], v[58:61]
	v_mfma_f32_16x16x32_bf16 v[54:57], v[146:149], v[224:227], v[54:57]
	v_mfma_f32_16x16x32_bf16 v[50:53], v[176:179], v[224:227], v[50:53]
	v_mfma_f32_16x16x32_bf16 v[14:17], v[146:149], v[232:235], v[14:17]
	v_mfma_f32_16x16x32_bf16 v[6:9], v[176:179], v[232:235], v[6:9]
	v_mfma_f32_16x16x32_bf16 v[10:13], v[146:149], v[240:243], v[10:13]
	v_mfma_f32_16x16x32_bf16 v[2:5], v[176:179], v[240:243], v[2:5]
	v_mfma_f32_16x16x32_bf16 v[62:65], v[172:175], v[218:221], v[62:65]
	v_mfma_f32_16x16x32_bf16 v[58:61], v[210:213], v[218:221], v[58:61]
	v_mfma_f32_16x16x32_bf16 v[54:57], v[172:175], v[228:231], v[54:57]
	v_mfma_f32_16x16x32_bf16 v[50:53], v[210:213], v[228:231], v[50:53]
	v_mfma_f32_16x16x32_bf16 v[14:17], v[172:175], v[236:239], v[14:17]
	v_mfma_f32_16x16x32_bf16 v[6:9], v[210:213], v[236:239], v[6:9]
	v_mfma_f32_16x16x32_bf16 v[10:13], v[172:175], v[244:247], v[10:13]
	v_mfma_f32_16x16x32_bf16 v[2:5], v[210:213], v[244:247], v[2:5]
	s_barrier
	s_setprio 0
	s_add_i32 s16, s16, 2
	s_add_u32 s8, s8, 0x100
	s_addc_u32 s9, s9, 0
	s_add_u32 s14, s14, 0x100
	s_addc_u32 s15, s15, 0
.LBB0_1040:
	ds_read_b128 v[130:133], v207
	ds_read_b128 v[134:137], v207 offset:1024
	ds_read_b128 v[138:141], v207 offset:2048
	ds_read_b128 v[142:145], v207 offset:3072
	ds_read_b128 v[146:149], v208
	ds_read_b128 v[172:175], v208 offset:1024
	ds_read_b128 v[176:179], v208 offset:2048
	ds_read_b128 v[210:213], v208 offset:3072
	s_add_u32 s10, s8, 0xffd50080
	s_addc_u32 s11, s9, -1
	s_cmpk_eq_i32 s16, 0xa8
	s_cselect_b32 s13, s25, s11
	s_cselect_b32 s12, s24, s10
	s_cselect_b32 s11, s41, s15
	s_cselect_b32 s10, s40, s14
	v_lshl_add_u64 v[180:181], s[8:9], 0, v[166:167]
	s_add_i32 m0, s48, 0xc000
	ds_read_b128 v[214:217], v202
	ds_read_b128 v[218:221], v202 offset:1024
	ds_read_b128 v[224:227], v202 offset:2048
	ds_read_b128 v[228:231], v202 offset:3072
	ds_read_b128 v[232:235], v202 offset:4096
	ds_read_b128 v[236:239], v202 offset:5120
	ds_read_b128 v[240:243], v202 offset:6144
	ds_read_b128 v[244:247], v202 offset:7168
	global_load_lds_dwordx4 v[180:181], off
	v_lshl_add_u64 v[180:181], s[8:9], 0, v[168:169]
	s_add_i32 m0, s48, 0xe000
	s_nop 0
	global_load_lds_dwordx4 v[180:181], off
	s_waitcnt vmcnt(8)
	s_waitcnt lgkmcnt(0)
	s_setprio 1
	s_barrier
	v_mfma_f32_16x16x32_bf16 v[90:93], v[130:133], v[214:217], v[90:93]
	v_mfma_f32_16x16x32_bf16 v[74:77], v[138:141], v[214:217], v[74:77]
	v_mfma_f32_16x16x32_bf16 v[46:49], v[130:133], v[224:227], v[46:49]
	v_mfma_f32_16x16x32_bf16 v[42:45], v[138:141], v[224:227], v[42:45]
	v_mfma_f32_16x16x32_bf16 v[126:129], v[130:133], v[232:235], v[126:129]
	v_mfma_f32_16x16x32_bf16 v[122:125], v[138:141], v[232:235], v[122:125]
	v_mfma_f32_16x16x32_bf16 v[110:113], v[130:133], v[240:243], v[110:113]
	v_mfma_f32_16x16x32_bf16 v[106:109], v[138:141], v[240:243], v[106:109]
	v_mfma_f32_16x16x32_bf16 v[90:93], v[134:137], v[218:221], v[90:93]
	v_mfma_f32_16x16x32_bf16 v[74:77], v[142:145], v[218:221], v[74:77]
	v_mfma_f32_16x16x32_bf16 v[46:49], v[134:137], v[228:231], v[46:49]
	v_mfma_f32_16x16x32_bf16 v[42:45], v[142:145], v[228:231], v[42:45]
	v_mfma_f32_16x16x32_bf16 v[126:129], v[134:137], v[236:239], v[126:129]
	v_mfma_f32_16x16x32_bf16 v[122:125], v[142:145], v[236:239], v[122:125]
	v_mfma_f32_16x16x32_bf16 v[110:113], v[134:137], v[244:247], v[110:113]
	v_mfma_f32_16x16x32_bf16 v[106:109], v[142:145], v[244:247], v[106:109]
	v_mfma_f32_16x16x32_bf16 v[70:73], v[146:149], v[214:217], v[70:73]
	v_mfma_f32_16x16x32_bf16 v[66:69], v[176:179], v[214:217], v[66:69]
	v_mfma_f32_16x16x32_bf16 v[34:37], v[146:149], v[224:227], v[34:37]
	v_mfma_f32_16x16x32_bf16 v[38:41], v[176:179], v[224:227], v[38:41]
	v_mfma_f32_16x16x32_bf16 v[118:121], v[146:149], v[232:235], v[118:121]
	v_mfma_f32_16x16x32_bf16 v[114:117], v[176:179], v[232:235], v[114:117]
	v_mfma_f32_16x16x32_bf16 v[102:105], v[146:149], v[240:243], v[102:105]
	v_mfma_f32_16x16x32_bf16 v[98:101], v[176:179], v[240:243], v[98:101]
	v_mfma_f32_16x16x32_bf16 v[70:73], v[172:175], v[218:221], v[70:73]
	v_mfma_f32_16x16x32_bf16 v[66:69], v[210:213], v[218:221], v[66:69]
	v_mfma_f32_16x16x32_bf16 v[34:37], v[172:175], v[228:231], v[34:37]
	v_mfma_f32_16x16x32_bf16 v[38:41], v[210:213], v[228:231], v[38:41]
	v_mfma_f32_16x16x32_bf16 v[118:121], v[172:175], v[236:239], v[118:121]
	v_mfma_f32_16x16x32_bf16 v[114:117], v[210:213], v[236:239], v[114:117]
	v_mfma_f32_16x16x32_bf16 v[102:105], v[172:175], v[244:247], v[102:105]
	v_mfma_f32_16x16x32_bf16 v[98:101], v[210:213], v[244:247], v[98:101]
	s_barrier
	s_setprio 0
	s_add_i32 s17, s57, s46
	v_lshl_add_u64 v[180:181], s[10:11], 0, v[150:151]
	s_mov_b32 m0, s17
	ds_read_b128 v[214:217], v202 offset:16384
	ds_read_b128 v[218:221], v202 offset:17408
	ds_read_b128 v[224:227], v202 offset:18432
	ds_read_b128 v[228:231], v202 offset:19456
	ds_read_b128 v[232:235], v202 offset:20480
	ds_read_b128 v[236:239], v202 offset:21504
	ds_read_b128 v[240:243], v202 offset:22528
	ds_read_b128 v[244:247], v202 offset:23552
	global_load_lds_dwordx4 v[180:181], off
	s_add_i32 m0, s17, 0x2000
	s_add_u32 s18, s10, 0x2b0000
	v_lshl_add_u64 v[248:249], s[10:11], 0, v[152:153]
	s_addc_u32 s19, s11, 0
	s_add_i32 s17, s58, s46
	global_load_lds_dwordx4 v[248:249], off
	v_lshl_add_u64 v[250:251], s[18:19], 0, v[150:151]
	s_mov_b32 m0, s17
	v_lshl_add_u64 v[252:253], s[12:13], 0, v[152:153]
	global_load_lds_dwordx4 v[250:251], off
	v_lshl_add_u64 v[250:251], s[18:19], 0, v[152:153]
	s_add_i32 m0, s17, 0x2000
	s_nop 0
	global_load_lds_dwordx4 v[250:251], off
	v_lshl_add_u64 v[250:251], s[12:13], 0, v[150:151]
	s_mov_b32 m0, s48
	s_nop 0
	global_load_lds_dwordx4 v[250:251], off
	s_mov_b32 m0, s49
	s_nop 0
	global_load_lds_dwordx4 v[252:253], off
	s_waitcnt vmcnt(8)
	s_waitcnt lgkmcnt(0)
	s_setprio 1
	s_barrier
	v_mfma_f32_16x16x32_bf16 v[94:97], v[130:133], v[214:217], v[94:97]
	v_mfma_f32_16x16x32_bf16 v[86:89], v[138:141], v[214:217], v[86:89]
	v_mfma_f32_16x16x32_bf16 v[82:85], v[130:133], v[224:227], v[82:85]
	v_mfma_f32_16x16x32_bf16 v[78:81], v[138:141], v[224:227], v[78:81]
	v_mfma_f32_16x16x32_bf16 v[30:33], v[130:133], v[232:235], v[30:33]
	v_mfma_f32_16x16x32_bf16 v[26:29], v[138:141], v[232:235], v[26:29]
	v_mfma_f32_16x16x32_bf16 v[22:25], v[130:133], v[240:243], v[22:25]
	v_mfma_f32_16x16x32_bf16 v[18:21], v[138:141], v[240:243], v[18:21]
	v_mfma_f32_16x16x32_bf16 v[94:97], v[134:137], v[218:221], v[94:97]
	v_mfma_f32_16x16x32_bf16 v[86:89], v[142:145], v[218:221], v[86:89]
	v_mfma_f32_16x16x32_bf16 v[82:85], v[134:137], v[228:231], v[82:85]
	v_mfma_f32_16x16x32_bf16 v[78:81], v[142:145], v[228:231], v[78:81]
	v_mfma_f32_16x16x32_bf16 v[30:33], v[134:137], v[236:239], v[30:33]
	v_mfma_f32_16x16x32_bf16 v[26:29], v[142:145], v[236:239], v[26:29]
	v_mfma_f32_16x16x32_bf16 v[22:25], v[134:137], v[244:247], v[22:25]
	v_mfma_f32_16x16x32_bf16 v[18:21], v[142:145], v[244:247], v[18:21]
	v_mfma_f32_16x16x32_bf16 v[62:65], v[146:149], v[214:217], v[62:65]
	v_mfma_f32_16x16x32_bf16 v[58:61], v[176:179], v[214:217], v[58:61]
	v_mfma_f32_16x16x32_bf16 v[54:57], v[146:149], v[224:227], v[54:57]
	v_mfma_f32_16x16x32_bf16 v[50:53], v[176:179], v[224:227], v[50:53]
	v_mfma_f32_16x16x32_bf16 v[14:17], v[146:149], v[232:235], v[14:17]
	v_mfma_f32_16x16x32_bf16 v[6:9], v[176:179], v[232:235], v[6:9]
	v_mfma_f32_16x16x32_bf16 v[10:13], v[146:149], v[240:243], v[10:13]
	v_mfma_f32_16x16x32_bf16 v[2:5], v[176:179], v[240:243], v[2:5]
	v_mfma_f32_16x16x32_bf16 v[62:65], v[172:175], v[218:221], v[62:65]
	v_mfma_f32_16x16x32_bf16 v[58:61], v[210:213], v[218:221], v[58:61]
	v_mfma_f32_16x16x32_bf16 v[54:57], v[172:175], v[228:231], v[54:57]
	v_mfma_f32_16x16x32_bf16 v[50:53], v[210:213], v[228:231], v[50:53]
	v_mfma_f32_16x16x32_bf16 v[14:17], v[172:175], v[236:239], v[14:17]
	v_mfma_f32_16x16x32_bf16 v[6:9], v[210:213], v[236:239], v[6:9]
	v_mfma_f32_16x16x32_bf16 v[10:13], v[172:175], v[244:247], v[10:13]
	v_mfma_f32_16x16x32_bf16 v[2:5], v[210:213], v[244:247], v[2:5]
	s_barrier
	s_setprio 0
	s_add_i32 s17, 0, 0x18000
	s_add_i32 s18, 0, 0x1c000
	v_add_u32_e32 v142, s17, v182
	v_add_u32_e32 v154, s18, v182
	ds_read_b128 v[130:133], v142
	ds_read_b128 v[134:137], v142 offset:1024
	ds_read_b128 v[138:141], v142 offset:2048
	ds_read_b128 v[142:145], v142 offset:3072
	ds_read_b128 v[146:149], v154
	ds_read_b128 v[172:175], v154 offset:1024
	ds_read_b128 v[176:179], v154 offset:2048
	ds_read_b128 v[210:213], v154 offset:3072
	s_add_u32 s12, s12, 0x2b0000
	s_addc_u32 s13, s13, 0
	s_mov_b32 m0, s50
	v_lshl_add_u64 v[188:189], s[12:13], 0, v[150:151]
	ds_read_b128 v[214:217], v202 offset:32768
	ds_read_b128 v[218:221], v202 offset:33792
	ds_read_b128 v[224:227], v202 offset:34816
	ds_read_b128 v[228:231], v202 offset:35840
	ds_read_b128 v[232:235], v202 offset:36864
	ds_read_b128 v[236:239], v202 offset:37888
	ds_read_b128 v[240:243], v202 offset:38912
	ds_read_b128 v[244:247], v202 offset:39936
	global_load_lds_dwordx4 v[188:189], off
	v_lshl_add_u64 v[188:189], s[12:13], 0, v[152:153]
	s_mov_b32 m0, s51
	s_nop 0
	global_load_lds_dwordx4 v[188:189], off
	s_waitcnt vmcnt(8)
	s_waitcnt lgkmcnt(0)
	s_setprio 1
	s_barrier
	v_mfma_f32_16x16x32_bf16 v[90:93], v[130:133], v[214:217], v[90:93]
	v_mfma_f32_16x16x32_bf16 v[74:77], v[138:141], v[214:217], v[74:77]
	v_mfma_f32_16x16x32_bf16 v[46:49], v[130:133], v[224:227], v[46:49]
	v_mfma_f32_16x16x32_bf16 v[42:45], v[138:141], v[224:227], v[42:45]
	v_mfma_f32_16x16x32_bf16 v[126:129], v[130:133], v[232:235], v[126:129]
	v_mfma_f32_16x16x32_bf16 v[122:125], v[138:141], v[232:235], v[122:125]
	v_mfma_f32_16x16x32_bf16 v[110:113], v[130:133], v[240:243], v[110:113]
	v_mfma_f32_16x16x32_bf16 v[106:109], v[138:141], v[240:243], v[106:109]
	v_mfma_f32_16x16x32_bf16 v[90:93], v[134:137], v[218:221], v[90:93]
	v_mfma_f32_16x16x32_bf16 v[74:77], v[142:145], v[218:221], v[74:77]
	v_mfma_f32_16x16x32_bf16 v[46:49], v[134:137], v[228:231], v[46:49]
	v_mfma_f32_16x16x32_bf16 v[42:45], v[142:145], v[228:231], v[42:45]
	v_mfma_f32_16x16x32_bf16 v[126:129], v[134:137], v[236:239], v[126:129]
	v_mfma_f32_16x16x32_bf16 v[122:125], v[142:145], v[236:239], v[122:125]
	v_mfma_f32_16x16x32_bf16 v[110:113], v[134:137], v[244:247], v[110:113]
	v_mfma_f32_16x16x32_bf16 v[106:109], v[142:145], v[244:247], v[106:109]
	v_mfma_f32_16x16x32_bf16 v[70:73], v[146:149], v[214:217], v[70:73]
	v_mfma_f32_16x16x32_bf16 v[66:69], v[176:179], v[214:217], v[66:69]
	v_mfma_f32_16x16x32_bf16 v[34:37], v[146:149], v[224:227], v[34:37]
	v_mfma_f32_16x16x32_bf16 v[38:41], v[176:179], v[224:227], v[38:41]
	v_mfma_f32_16x16x32_bf16 v[118:121], v[146:149], v[232:235], v[118:121]
	v_mfma_f32_16x16x32_bf16 v[114:117], v[176:179], v[232:235], v[114:117]
	v_mfma_f32_16x16x32_bf16 v[102:105], v[146:149], v[240:243], v[102:105]
	v_mfma_f32_16x16x32_bf16 v[98:101], v[176:179], v[240:243], v[98:101]
	v_mfma_f32_16x16x32_bf16 v[70:73], v[172:175], v[218:221], v[70:73]
	v_mfma_f32_16x16x32_bf16 v[66:69], v[210:213], v[218:221], v[66:69]
	v_mfma_f32_16x16x32_bf16 v[34:37], v[172:175], v[228:231], v[34:37]
	v_mfma_f32_16x16x32_bf16 v[38:41], v[210:213], v[228:231], v[38:41]
	v_mfma_f32_16x16x32_bf16 v[118:121], v[172:175], v[236:239], v[118:121]
	v_mfma_f32_16x16x32_bf16 v[114:117], v[210:213], v[236:239], v[114:117]
	v_mfma_f32_16x16x32_bf16 v[102:105], v[172:175], v[244:247], v[102:105]
	v_mfma_f32_16x16x32_bf16 v[98:101], v[210:213], v[244:247], v[98:101]
	s_barrier
	s_setprio 0
	s_add_i32 s12, s17, s46
	v_lshl_add_u64 v[180:181], v[180:181], 0, s[30:31]
	s_mov_b32 m0, s12
	ds_read_b128 v[214:217], v202 offset:49152
	ds_read_b128 v[218:221], v202 offset:50176
	ds_read_b128 v[224:227], v202 offset:51200
	ds_read_b128 v[228:231], v202 offset:52224
	ds_read_b128 v[232:235], v202 offset:53248
	ds_read_b128 v[236:239], v202 offset:54272
	ds_read_b128 v[240:243], v202 offset:55296
	ds_read_b128 v[244:247], v202 offset:56320
	global_load_lds_dwordx4 v[180:181], off
	s_add_i32 m0, s12, 0x2000
	s_add_u32 s10, s10, 0x2b0080
	v_lshl_add_u64 v[180:181], v[248:249], 0, s[30:31]
	s_addc_u32 s11, s11, 0
	s_add_i32 s12, s18, s46
	global_load_lds_dwordx4 v[180:181], off
	v_lshl_add_u64 v[180:181], s[10:11], 0, v[150:151]
	s_mov_b32 m0, s12
	s_nop 0
	global_load_lds_dwordx4 v[180:181], off
	v_lshl_add_u64 v[180:181], s[10:11], 0, v[152:153]
	s_add_i32 m0, s12, 0x2000
	s_nop 0
	global_load_lds_dwordx4 v[180:181], off
	v_lshl_add_u64 v[180:181], v[250:251], 0, s[30:31]
	s_mov_b32 m0, s52
	s_nop 0
	global_load_lds_dwordx4 v[180:181], off
	v_lshl_add_u64 v[180:181], v[252:253], 0, s[30:31]
	s_mov_b32 m0, s53
	s_nop 0
	global_load_lds_dwordx4 v[180:181], off
	s_waitcnt vmcnt(8)
	s_waitcnt lgkmcnt(0)
	s_nop 0
	s_setprio 1
	s_barrier
	v_mfma_f32_16x16x32_bf16 v[94:97], v[130:133], v[214:217], v[94:97]
	v_mfma_f32_16x16x32_bf16 v[86:89], v[138:141], v[214:217], v[86:89]
	v_mfma_f32_16x16x32_bf16 v[82:85], v[130:133], v[224:227], v[82:85]
	v_mfma_f32_16x16x32_bf16 v[78:81], v[138:141], v[224:227], v[78:81]
	v_mfma_f32_16x16x32_bf16 v[30:33], v[130:133], v[232:235], v[30:33]
	v_mfma_f32_16x16x32_bf16 v[26:29], v[138:141], v[232:235], v[26:29]
	v_mfma_f32_16x16x32_bf16 v[22:25], v[130:133], v[240:243], v[22:25]
	v_mfma_f32_16x16x32_bf16 v[18:21], v[138:141], v[240:243], v[18:21]
	v_mfma_f32_16x16x32_bf16 v[94:97], v[134:137], v[218:221], v[94:97]
	v_mfma_f32_16x16x32_bf16 v[86:89], v[142:145], v[218:221], v[86:89]
	v_mfma_f32_16x16x32_bf16 v[82:85], v[134:137], v[228:231], v[82:85]
	v_mfma_f32_16x16x32_bf16 v[78:81], v[142:145], v[228:231], v[78:81]
	v_mfma_f32_16x16x32_bf16 v[30:33], v[134:137], v[236:239], v[30:33]
	v_mfma_f32_16x16x32_bf16 v[26:29], v[142:145], v[236:239], v[26:29]
	v_mfma_f32_16x16x32_bf16 v[22:25], v[134:137], v[244:247], v[22:25]
	v_mfma_f32_16x16x32_bf16 v[18:21], v[142:145], v[244:247], v[18:21]
	v_mfma_f32_16x16x32_bf16 v[62:65], v[146:149], v[214:217], v[62:65]
	v_mfma_f32_16x16x32_bf16 v[58:61], v[176:179], v[214:217], v[58:61]
	v_mfma_f32_16x16x32_bf16 v[54:57], v[146:149], v[224:227], v[54:57]
	v_mfma_f32_16x16x32_bf16 v[50:53], v[176:179], v[224:227], v[50:53]
	v_mfma_f32_16x16x32_bf16 v[14:17], v[146:149], v[232:235], v[14:17]
	v_mfma_f32_16x16x32_bf16 v[6:9], v[176:179], v[232:235], v[6:9]
	v_mfma_f32_16x16x32_bf16 v[10:13], v[146:149], v[240:243], v[10:13]
	v_mfma_f32_16x16x32_bf16 v[2:5], v[176:179], v[240:243], v[2:5]
	v_mfma_f32_16x16x32_bf16 v[62:65], v[172:175], v[218:221], v[62:65]
	v_mfma_f32_16x16x32_bf16 v[58:61], v[210:213], v[218:221], v[58:61]
	v_mfma_f32_16x16x32_bf16 v[54:57], v[172:175], v[228:231], v[54:57]
	v_mfma_f32_16x16x32_bf16 v[50:53], v[210:213], v[228:231], v[50:53]
	v_mfma_f32_16x16x32_bf16 v[14:17], v[172:175], v[236:239], v[14:17]
	v_mfma_f32_16x16x32_bf16 v[6:9], v[210:213], v[236:239], v[6:9]
	v_mfma_f32_16x16x32_bf16 v[10:13], v[172:175], v[244:247], v[10:13]
	v_mfma_f32_16x16x32_bf16 v[2:5], v[210:213], v[244:247], v[2:5]
	s_barrier
	s_setprio 0
	s_add_i32 s16, s16, 2
	s_add_u32 s8, s8, 0x100
	s_addc_u32 s9, s9, 0
	s_add_u32 s14, s14, 0x100
	s_addc_u32 s15, s15, 0
	s_cmpk_gt_u32 s16, 0xa9
	s_cbranch_scc0 .LBB0_1040
	s_and_b64 vcc, exec, s[34:35]
	s_cbranch_vccz .LBB0_1043
	s_barrier
